# all 16 K-loop LDS-DMA loads per iteration in SGPR-base form (no VALU address adds; +0x80 / old-base variants computed by SALU into spare SGPRs)
# speedup vs baseline: 1.0070x; 1.0041x over previous
; #define PG8_STAGE(bufoff, gbase, voff) do { _Pragma("unroll") for (int _i = 0; _i < 2; ++_i) \
;         __builtin_amdgcn_global_load_lds((const unsigned*)((const char*)(gbase) + (voff)[_i]), (PG8_LAS unsigned*)(lds + (bufoff) + ldsw + _i * 8192), 16, 0, 0); } while (0)
; #define PG8_LDA(dst, b, h) do { _Pragma("unroll") for (int m = 0; m < 4; ++m) _Pragma("unroll") for (int k = 0; k < 2; ++k) dst[m][k] = *(const PG8_LAS bf16x8*)(lds + PG8_SA(b, h) + aoff + m * 2048 + k * 1024); } while (0)
; #define PG8_LDB(dst, b, h) do { _Pragma("unroll") for (int n = 0; n < 2; ++n) _Pragma("unroll") for (int k = 0; k < 2; ++k) dst[n][k] = *(const PG8_LAS bf16x8*)(lds + PG8_SB(b, h) + boff + n * 2048 + k * 1024); } while (0)
; #define PG8_MMA(ai, bj, At, Bt) do { __builtin_amdgcn_s_setprio(1); _Pragma("unroll") for (int m = 0; m < 4; ++m) _Pragma("unroll") for (int n = 0; n < 2; ++n) _Pragma("unroll") for (int k = 0; k < 2; ++k) \
;         acc[ai][bj][m][n] = __builtin_amdgcn_mfma_f32_16x16x32_bf16(Bt[n][k], At[m][k], acc[ai][bj][m][n], 0, 0, 0); __builtin_amdgcn_s_setprio(0); } while (0)
; #define PG8_WAIT_V(n) asm volatile("s_waitcnt vmcnt(" #n ")" ::: "memory")
; #define PG8_WAIT_L(n) asm volatile("s_waitcnt lgkmcnt(" #n ")" ::: "memory")
; #define PG8_BAR __builtin_amdgcn_s_barrier()
; template <class Epi, class Sched, bool ALIGN_EPI = false, bool SP2 = false>
; __device__ __forceinline__ void gemm_phase(PG8_LAS unsigned char* lds, const Gemm g, const Sched& S, const Epi& E, int wave_s) {
;     ...
;             const char* a1 = cA + (size_t)(t + 1) * kstep;
;             const char* a2 = last ? nA : cA + (size_t)(t + 2) * kstep; const char* b2 = last ? nB : cB + (size_t)(t + 2) * kstep;
;             const char* a3 = a2 + kstep; const char* b3 = b2 + kstep;
;             if (last && has_next) S.a_ready(nxt);
;             if constexpr (SP2) {
;             PG8_LDB(B0, 0, 0); PG8_LDB(B1, 0, 1); PG8_SCHED; PG8_LDA(At, 0, 0); PG8_STAGE(PG8_SA(1, 1), a1 + hstep, voffA);
;             PG8_WAIT_V(8); PG8_WAIT_L(0); PG8_BAR; PG8_MMA(0, 0, At, B0); PG8_MMA(0, 1, At, B1); PG8_BAR; PG8_SCHED;
;             PG8_LDA(At, 0, 1); PG8_STAGE(PG8_SB(0, 0), b2, voffB); PG8_STAGE(PG8_SB(0, 1), b2 + hstep, voffB); PG8_STAGE(PG8_SA(0, 0), a2, voffA);
;             PG8_WAIT_V(8); PG8_WAIT_L(0); PG8_BAR; PG8_MMA(1, 0, At, B0); PG8_MMA(1, 1, At, B1); PG8_BAR; PG8_SCHED;
.LBB0_41:
	ds_read_b128 v[144:147], v158 offset:3072
	ds_read_b128 v[148:151], v158 offset:2048
	ds_read_b128 v[152:155], v158 offset:1024
	ds_read_b128 v[160:163], v158
	ds_read_b128 v[164:167], v157 offset:3072
	ds_read_b128 v[168:171], v157 offset:2048
	ds_read_b128 v[172:175], v157 offset:1024
	ds_read_b128 v[176:179], v157
	s_add_u32 s48, s46, 0xfff00080
	s_addc_u32 s49, s47, -1
	s_cmp_eq_u32 s86, 60
	s_cselect_b32 s51, s31, s49
	s_cselect_b32 s50, s72, s48
	s_cselect_b32 s49, s35, s85
	s_cselect_b32 s48, s73, s84
	s_mov_b32 m0, s74
	s_nop 0
	ds_read_b128 v[180:183], v159
	ds_read_b128 v[184:187], v159 offset:1024
	ds_read_b128 v[188:191], v159 offset:2048
	ds_read_b128 v[192:195], v159 offset:3072
	ds_read_b128 v[196:199], v159 offset:4096
	ds_read_b128 v[200:203], v159 offset:5120
	ds_read_b128 v[204:207], v159 offset:6144
	ds_read_b128 v[208:211], v159 offset:7168
	global_load_lds_dwordx4 v138, s[46:47]
	s_nop 0
	s_mov_b32 m0, s75
	s_nop 0
	global_load_lds_dwordx4 v140, s[46:47]
	s_waitcnt vmcnt(8)
	s_waitcnt lgkmcnt(0)
	s_barrier
	v_mfma_f32_16x16x32_bf16 v[124:127], v[176:179], v[180:183], v[124:127]
	v_mfma_f32_16x16x32_bf16 v[124:127], v[172:175], v[184:187], v[124:127]
	v_mfma_f32_16x16x32_bf16 v[120:123], v[164:167], v[184:187], v[120:123]
	v_mfma_f32_16x16x32_bf16 v[120:123], v[168:171], v[180:183], v[120:123]
	v_mfma_f32_16x16x32_bf16 v[104:107], v[168:171], v[188:191], v[104:107]
	v_mfma_f32_16x16x32_bf16 v[104:107], v[164:167], v[192:195], v[104:107]
	v_mfma_f32_16x16x32_bf16 v[108:111], v[172:175], v[192:195], v[108:111]
	v_mfma_f32_16x16x32_bf16 v[108:111], v[176:179], v[188:191], v[108:111]
	v_mfma_f32_16x16x32_bf16 v[92:95], v[176:179], v[196:199], v[92:95]
	v_mfma_f32_16x16x32_bf16 v[92:95], v[172:175], v[200:203], v[92:95]
	v_mfma_f32_16x16x32_bf16 v[88:91], v[164:167], v[200:203], v[88:91]
	v_mfma_f32_16x16x32_bf16 v[88:91], v[168:171], v[196:199], v[88:91]
	v_mfma_f32_16x16x32_bf16 v[56:59], v[168:171], v[204:207], v[56:59]
	v_mfma_f32_16x16x32_bf16 v[56:59], v[164:167], v[208:211], v[56:59]
	v_mfma_f32_16x16x32_bf16 v[64:67], v[172:175], v[208:211], v[64:67]
	v_mfma_f32_16x16x32_bf16 v[64:67], v[176:179], v[204:207], v[64:67]
	v_mfma_f32_16x16x32_bf16 v[116:119], v[160:163], v[180:183], v[116:119]
	v_mfma_f32_16x16x32_bf16 v[116:119], v[152:155], v[184:187], v[116:119]
	v_mfma_f32_16x16x32_bf16 v[112:115], v[144:147], v[184:187], v[112:115]
	v_mfma_f32_16x16x32_bf16 v[112:115], v[148:151], v[180:183], v[112:115]
	v_mfma_f32_16x16x32_bf16 v[96:99], v[148:151], v[188:191], v[96:99]
	v_mfma_f32_16x16x32_bf16 v[96:99], v[144:147], v[192:195], v[96:99]
	v_mfma_f32_16x16x32_bf16 v[100:103], v[152:155], v[192:195], v[100:103]
	v_mfma_f32_16x16x32_bf16 v[100:103], v[160:163], v[188:191], v[100:103]
	v_mfma_f32_16x16x32_bf16 v[84:87], v[160:163], v[196:199], v[84:87]
	v_mfma_f32_16x16x32_bf16 v[84:87], v[152:155], v[200:203], v[84:87]
	v_mfma_f32_16x16x32_bf16 v[80:83], v[144:147], v[200:203], v[80:83]
	v_mfma_f32_16x16x32_bf16 v[80:83], v[148:151], v[196:199], v[80:83]
	v_mfma_f32_16x16x32_bf16 v[48:51], v[148:151], v[204:207], v[48:51]
	v_mfma_f32_16x16x32_bf16 v[48:51], v[144:147], v[208:211], v[48:51]
	v_mfma_f32_16x16x32_bf16 v[52:55], v[152:155], v[208:211], v[52:55]
	v_mfma_f32_16x16x32_bf16 v[52:55], v[160:163], v[204:207], v[52:55]
	s_barrier
	s_mov_b32 m0, s76
	s_nop 0
	s_add_u32 s88, s48, 0x100000
	ds_read_b128 v[180:183], v159 offset:16384
	ds_read_b128 v[184:187], v159 offset:17408
	ds_read_b128 v[188:191], v159 offset:18432
	ds_read_b128 v[192:195], v159 offset:19456
	ds_read_b128 v[196:199], v159 offset:20480
	ds_read_b128 v[200:203], v159 offset:21504
	ds_read_b128 v[204:207], v159 offset:22528
	ds_read_b128 v[208:211], v159 offset:23552
	global_load_lds_dwordx4 v132, s[48:49]
	s_nop 0
	s_mov_b32 m0, s77
	s_addc_u32 s89, s49, 0
	global_load_lds_dwordx4 v128, s[48:49]
	s_nop 0
	s_mov_b32 m0, s78
	s_nop 0
	global_load_lds_dwordx4 v132, s[88:89]
	s_nop 0
	s_mov_b32 m0, s79
	s_nop 0
	global_load_lds_dwordx4 v128, s[88:89]
	s_nop 0
	s_mov_b32 m0, s43
	s_nop 0
	global_load_lds_dwordx4 v134, s[50:51]
	s_mov_b32 m0, s57
	s_nop 0
	global_load_lds_dwordx4 v130, s[50:51]
	s_waitcnt vmcnt(8)
	s_waitcnt lgkmcnt(0)
	s_barrier
	v_mfma_f32_16x16x32_bf16 v[76:79], v[176:179], v[180:183], v[76:79]
	v_mfma_f32_16x16x32_bf16 v[76:79], v[172:175], v[184:187], v[76:79]
	v_mfma_f32_16x16x32_bf16 v[72:75], v[164:167], v[184:187], v[72:75]
	v_mfma_f32_16x16x32_bf16 v[72:75], v[168:171], v[180:183], v[72:75]
	v_mfma_f32_16x16x32_bf16 v[40:43], v[168:171], v[188:191], v[40:43]
	v_mfma_f32_16x16x32_bf16 v[40:43], v[164:167], v[192:195], v[40:43]
	v_mfma_f32_16x16x32_bf16 v[44:47], v[172:175], v[192:195], v[44:47]
	v_mfma_f32_16x16x32_bf16 v[44:47], v[176:179], v[188:191], v[44:47]
	v_mfma_f32_16x16x32_bf16 v[28:31], v[176:179], v[196:199], v[28:31]
	v_mfma_f32_16x16x32_bf16 v[28:31], v[172:175], v[200:203], v[28:31]
	v_mfma_f32_16x16x32_bf16 v[24:27], v[164:167], v[200:203], v[24:27]
	v_mfma_f32_16x16x32_bf16 v[24:27], v[168:171], v[196:199], v[24:27]
	v_mfma_f32_16x16x32_bf16 v[8:11], v[168:171], v[204:207], v[8:11]
	v_mfma_f32_16x16x32_bf16 v[8:11], v[164:167], v[208:211], v[8:11]
	v_mfma_f32_16x16x32_bf16 v[12:15], v[172:175], v[208:211], v[12:15]
	v_mfma_f32_16x16x32_bf16 v[12:15], v[176:179], v[204:207], v[12:15]
	v_mfma_f32_16x16x32_bf16 v[68:71], v[160:163], v[180:183], v[68:71]
	v_mfma_f32_16x16x32_bf16 v[68:71], v[152:155], v[184:187], v[68:71]
	v_mfma_f32_16x16x32_bf16 v[60:63], v[144:147], v[184:187], v[60:63]
	v_mfma_f32_16x16x32_bf16 v[60:63], v[148:151], v[180:183], v[60:63]
	v_mfma_f32_16x16x32_bf16 v[32:35], v[148:151], v[188:191], v[32:35]
	v_mfma_f32_16x16x32_bf16 v[32:35], v[144:147], v[192:195], v[32:35]
	v_mfma_f32_16x16x32_bf16 v[36:39], v[152:155], v[192:195], v[36:39]
	v_mfma_f32_16x16x32_bf16 v[36:39], v[160:163], v[188:191], v[36:39]
	v_mfma_f32_16x16x32_bf16 v[20:23], v[160:163], v[196:199], v[20:23]
	v_mfma_f32_16x16x32_bf16 v[20:23], v[152:155], v[200:203], v[20:23]
	v_mfma_f32_16x16x32_bf16 v[16:19], v[144:147], v[200:203], v[16:19]
	v_mfma_f32_16x16x32_bf16 v[16:19], v[148:151], v[196:199], v[16:19]
	v_mfma_f32_16x16x32_bf16 v[0:3], v[148:151], v[204:207], v[0:3]
	v_mfma_f32_16x16x32_bf16 v[0:3], v[144:147], v[208:211], v[0:3]
	v_mfma_f32_16x16x32_bf16 v[4:7], v[152:155], v[208:211], v[4:7]
	v_mfma_f32_16x16x32_bf16 v[4:7], v[160:163], v[204:207], v[4:7]
	s_barrier
; #define PG8_LAS __attribute__((address_space(3)))
; #define PG8_STAGE(bufoff, gbase, voff) do { _Pragma("unroll") for (int _i = 0; _i < 2; ++_i) \
;         __builtin_amdgcn_global_load_lds((const unsigned*)((const char*)(gbase) + (voff)[_i]), (PG8_LAS unsigned*)(lds + (bufoff) + ldsw + _i * 8192), 16, 0, 0); } while (0)
; #define PG8_LDA(dst, b, h) do { _Pragma("unroll") for (int m = 0; m < 4; ++m) _Pragma("unroll") for (int k = 0; k < 2; ++k) dst[m][k] = *(const PG8_LAS bf16x8*)(lds + PG8_SA(b, h) + aoff + m * 2048 + k * 1024); } while (0)
; #define PG8_LDB(dst, b, h) do { _Pragma("unroll") for (int n = 0; n < 2; ++n) _Pragma("unroll") for (int k = 0; k < 2; ++k) dst[n][k] = *(const PG8_LAS bf16x8*)(lds + PG8_SB(b, h) + boff + n * 2048 + k * 1024); } while (0)
; #define PG8_WAIT_V(n) asm volatile("s_waitcnt vmcnt(" #n ")" ::: "memory")
; #define PG8_WAIT_L(n) asm volatile("s_waitcnt lgkmcnt(" #n ")" ::: "memory")
; #define PG8_BAR __builtin_amdgcn_s_barrier()
; #define PG8_SCHED __builtin_amdgcn_sched_barrier(0)
; template <class Epi, class Sched, bool ALIGN_EPI = false, bool SP2 = false>
; __device__ __forceinline__ void gemm_phase(PG8_LAS unsigned char* lds, const Gemm g, const Sched& S, const Epi& E, int wave_s) {
;     ...
;         for (int t = 0; t < nt; t += 2) {
;             const bool last = (t == nt - 2);
;             if constexpr (Epi::NEED_RS) { if (t == 0 && wid < 4) __builtin_amdgcn_global_load_lds((const unsigned*)(E.rstd + cur.pm * BM + wid * 64 + lane), (PG8_LAS unsigned*)(rsl + wid * 64), 4, 0, 0); }
;             const char* a1 = cA + (size_t)(t + 1) * kstep;
;             const char* a2 = last ? nA : cA + (size_t)(t + 2) * kstep; const char* b2 = last ? nB : cB + (size_t)(t + 2) * kstep;
;             const char* a3 = a2 + kstep; const char* b3 = b2 + kstep;
;     ...
;             PG8_LDB(B0, 1, 0); PG8_LDB(B1, 1, 1); PG8_SCHED; PG8_LDA(At, 1, 0); PG8_STAGE(PG8_SA(0, 1), a2 + hstep, voffA);
;             PG8_WAIT_V(8); PG8_WAIT_L(0); PG8_BAR; PG8_MMA(0, 0, At, B0); PG8_MMA(0, 1, At, B1); PG8_BAR; PG8_SCHED;
;             PG8_LDA(At, 1, 1); PG8_STAGE(PG8_SB(1, 0), b3, voffB); PG8_STAGE(PG8_SB(1, 1), b3 + hstep, voffB); PG8_STAGE(PG8_SA(1, 0), a3, voffA);
;             PG8_WAIT_V(8); PG8_WAIT_L(0); PG8_BAR; PG8_MMA(1, 0, At, B0); PG8_MMA(1, 1, At, B1); PG8_BAR; PG8_SCHED;
	ds_read_b128 v[144:147], v142
	ds_read_b128 v[148:151], v142 offset:1024
	ds_read_b128 v[152:155], v142 offset:2048
	ds_read_b128 v[160:163], v142 offset:3072
	ds_read_b128 v[164:167], v143
	ds_read_b128 v[168:171], v143 offset:1024
	ds_read_b128 v[172:175], v143 offset:2048
	ds_read_b128 v[176:179], v143 offset:3072
	s_add_u32 s50, s50, 0x100000
	s_addc_u32 s51, s51, 0
	s_mov_b32 m0, s58
	s_nop 0
	ds_read_b128 v[180:183], v159 offset:32768
	ds_read_b128 v[184:187], v159 offset:33792
	ds_read_b128 v[188:191], v159 offset:34816
	ds_read_b128 v[192:195], v159 offset:35840
	ds_read_b128 v[196:199], v159 offset:36864
	ds_read_b128 v[200:203], v159 offset:37888
	ds_read_b128 v[204:207], v159 offset:38912
	ds_read_b128 v[208:211], v159 offset:39936
	global_load_lds_dwordx4 v134, s[50:51]
	s_nop 0
	s_mov_b32 m0, s59
	s_nop 0
	global_load_lds_dwordx4 v130, s[50:51]
	s_waitcnt vmcnt(8)
	s_waitcnt lgkmcnt(0)
	s_barrier
	v_mfma_f32_16x16x32_bf16 v[124:127], v[144:147], v[180:183], v[124:127]
	v_mfma_f32_16x16x32_bf16 v[124:127], v[148:151], v[184:187], v[124:127]
	v_mfma_f32_16x16x32_bf16 v[120:123], v[160:163], v[184:187], v[120:123]
	v_mfma_f32_16x16x32_bf16 v[120:123], v[152:155], v[180:183], v[120:123]
	v_mfma_f32_16x16x32_bf16 v[104:107], v[152:155], v[188:191], v[104:107]
	v_mfma_f32_16x16x32_bf16 v[104:107], v[160:163], v[192:195], v[104:107]
	v_mfma_f32_16x16x32_bf16 v[108:111], v[148:151], v[192:195], v[108:111]
	v_mfma_f32_16x16x32_bf16 v[108:111], v[144:147], v[188:191], v[108:111]
	v_mfma_f32_16x16x32_bf16 v[92:95], v[144:147], v[196:199], v[92:95]
	v_mfma_f32_16x16x32_bf16 v[92:95], v[148:151], v[200:203], v[92:95]
	v_mfma_f32_16x16x32_bf16 v[88:91], v[160:163], v[200:203], v[88:91]
	v_mfma_f32_16x16x32_bf16 v[88:91], v[152:155], v[196:199], v[88:91]
	v_mfma_f32_16x16x32_bf16 v[56:59], v[152:155], v[204:207], v[56:59]
	v_mfma_f32_16x16x32_bf16 v[56:59], v[160:163], v[208:211], v[56:59]
	v_mfma_f32_16x16x32_bf16 v[64:67], v[148:151], v[208:211], v[64:67]
	v_mfma_f32_16x16x32_bf16 v[64:67], v[144:147], v[204:207], v[64:67]
	v_mfma_f32_16x16x32_bf16 v[116:119], v[164:167], v[180:183], v[116:119]
	v_mfma_f32_16x16x32_bf16 v[116:119], v[168:171], v[184:187], v[116:119]
	v_mfma_f32_16x16x32_bf16 v[112:115], v[176:179], v[184:187], v[112:115]
	v_mfma_f32_16x16x32_bf16 v[112:115], v[172:175], v[180:183], v[112:115]
	v_mfma_f32_16x16x32_bf16 v[96:99], v[172:175], v[188:191], v[96:99]
	v_mfma_f32_16x16x32_bf16 v[96:99], v[176:179], v[192:195], v[96:99]
	v_mfma_f32_16x16x32_bf16 v[100:103], v[168:171], v[192:195], v[100:103]
	v_mfma_f32_16x16x32_bf16 v[100:103], v[164:167], v[188:191], v[100:103]
	v_mfma_f32_16x16x32_bf16 v[84:87], v[164:167], v[196:199], v[84:87]
	v_mfma_f32_16x16x32_bf16 v[84:87], v[168:171], v[200:203], v[84:87]
	v_mfma_f32_16x16x32_bf16 v[80:83], v[176:179], v[200:203], v[80:83]
	v_mfma_f32_16x16x32_bf16 v[80:83], v[172:175], v[196:199], v[80:83]
	v_mfma_f32_16x16x32_bf16 v[48:51], v[172:175], v[204:207], v[48:51]
	v_mfma_f32_16x16x32_bf16 v[48:51], v[176:179], v[208:211], v[48:51]
	v_mfma_f32_16x16x32_bf16 v[52:55], v[168:171], v[208:211], v[52:55]
	v_mfma_f32_16x16x32_bf16 v[52:55], v[164:167], v[204:207], v[52:55]
	s_barrier
	s_mov_b32 m0, s80
	s_nop 0
	s_add_u32 s94, s48, 0x80
	s_addc_u32 s95, s49, 0
	s_add_u32 s48, s48, 0x100080
	ds_read_b128 v[180:183], v159 offset:49152
	ds_read_b128 v[184:187], v159 offset:50176
	ds_read_b128 v[188:191], v159 offset:51200
	ds_read_b128 v[192:195], v159 offset:52224
	ds_read_b128 v[196:199], v159 offset:53248
	ds_read_b128 v[200:203], v159 offset:54272
	ds_read_b128 v[204:207], v159 offset:55296
	ds_read_b128 v[208:211], v159 offset:56320
	global_load_lds_dwordx4 v132, s[94:95]
	s_nop 0
	s_mov_b32 m0, s81
	s_addc_u32 s49, s49, 0
	global_load_lds_dwordx4 v128, s[94:95]
	s_nop 0
	s_mov_b32 m0, s82
	s_nop 0
	global_load_lds_dwordx4 v132, s[48:49]
	s_nop 0
	s_mov_b32 m0, s83
	s_nop 0
	global_load_lds_dwordx4 v128, s[48:49]
	s_nop 0
	s_mov_b32 m0, s64
	s_nop 0
	s_add_u32 s96, s50, 0xfff00080
	s_addc_u32 s97, s51, -1
	global_load_lds_dwordx4 v134, s[96:97]
	s_nop 0
	s_mov_b32 m0, s65
	s_nop 0
	global_load_lds_dwordx4 v130, s[96:97]
	s_waitcnt vmcnt(8)
	s_waitcnt lgkmcnt(0)
	s_barrier
	v_mfma_f32_16x16x32_bf16 v[76:79], v[144:147], v[180:183], v[76:79]
	v_mfma_f32_16x16x32_bf16 v[76:79], v[148:151], v[184:187], v[76:79]
	v_mfma_f32_16x16x32_bf16 v[72:75], v[160:163], v[184:187], v[72:75]
	v_mfma_f32_16x16x32_bf16 v[72:75], v[152:155], v[180:183], v[72:75]
	v_mfma_f32_16x16x32_bf16 v[40:43], v[152:155], v[188:191], v[40:43]
	v_mfma_f32_16x16x32_bf16 v[40:43], v[160:163], v[192:195], v[40:43]
	v_mfma_f32_16x16x32_bf16 v[44:47], v[148:151], v[192:195], v[44:47]
	v_mfma_f32_16x16x32_bf16 v[44:47], v[144:147], v[188:191], v[44:47]
	v_mfma_f32_16x16x32_bf16 v[28:31], v[144:147], v[196:199], v[28:31]
	v_mfma_f32_16x16x32_bf16 v[28:31], v[148:151], v[200:203], v[28:31]
	v_mfma_f32_16x16x32_bf16 v[24:27], v[160:163], v[200:203], v[24:27]
	v_mfma_f32_16x16x32_bf16 v[24:27], v[152:155], v[196:199], v[24:27]
	v_mfma_f32_16x16x32_bf16 v[8:11], v[152:155], v[204:207], v[8:11]
	v_mfma_f32_16x16x32_bf16 v[8:11], v[160:163], v[208:211], v[8:11]
	v_mfma_f32_16x16x32_bf16 v[12:15], v[148:151], v[208:211], v[12:15]
	v_mfma_f32_16x16x32_bf16 v[12:15], v[144:147], v[204:207], v[12:15]
	v_mfma_f32_16x16x32_bf16 v[68:71], v[164:167], v[180:183], v[68:71]
	v_mfma_f32_16x16x32_bf16 v[68:71], v[168:171], v[184:187], v[68:71]
	v_mfma_f32_16x16x32_bf16 v[60:63], v[176:179], v[184:187], v[60:63]
	v_mfma_f32_16x16x32_bf16 v[60:63], v[172:175], v[180:183], v[60:63]
	v_mfma_f32_16x16x32_bf16 v[32:35], v[172:175], v[188:191], v[32:35]
	v_mfma_f32_16x16x32_bf16 v[32:35], v[176:179], v[192:195], v[32:35]
	v_mfma_f32_16x16x32_bf16 v[36:39], v[168:171], v[192:195], v[36:39]
	v_mfma_f32_16x16x32_bf16 v[36:39], v[164:167], v[188:191], v[36:39]
	v_mfma_f32_16x16x32_bf16 v[20:23], v[164:167], v[196:199], v[20:23]
	v_mfma_f32_16x16x32_bf16 v[20:23], v[168:171], v[200:203], v[20:23]
	v_mfma_f32_16x16x32_bf16 v[16:19], v[176:179], v[200:203], v[16:19]
	v_mfma_f32_16x16x32_bf16 v[16:19], v[172:175], v[196:199], v[16:19]
	v_mfma_f32_16x16x32_bf16 v[0:3], v[172:175], v[204:207], v[0:3]
	v_mfma_f32_16x16x32_bf16 v[0:3], v[176:179], v[208:211], v[0:3]
	v_mfma_f32_16x16x32_bf16 v[4:7], v[168:171], v[208:211], v[4:7]
	v_mfma_f32_16x16x32_bf16 v[4:7], v[164:167], v[204:207], v[4:7]
	s_barrier
	s_add_i32 s86, s86, 2
	s_add_u32 s46, s46, 0x100
	s_addc_u32 s47, s47, 0
	s_add_u32 s84, s84, 0x100
	s_addc_u32 s85, s85, 0
	s_cmp_gt_u32 s86, 61
	s_cbranch_scc0 .LBB0_41
	s_and_b64 vcc, exec, s[14:15]
	s_cbranch_vccz .LBB0_44
	s_barrier

; #define PG8_STAGE(bufoff, gbase, voff) do { _Pragma("unroll") for (int _i = 0; _i < 2; ++_i) \
;         __builtin_amdgcn_global_load_lds((const unsigned*)((const char*)(gbase) + (voff)[_i]), (PG8_LAS unsigned*)(lds + (bufoff) + ldsw + _i * 8192), 16, 0, 0); } while (0)
; #define PG8_LDA(dst, b, h) do { _Pragma("unroll") for (int m = 0; m < 4; ++m) _Pragma("unroll") for (int k = 0; k < 2; ++k) dst[m][k] = *(const PG8_LAS bf16x8*)(lds + PG8_SA(b, h) + aoff + m * 2048 + k * 1024); } while (0)
; #define PG8_LDB(dst, b, h) do { _Pragma("unroll") for (int n = 0; n < 2; ++n) _Pragma("unroll") for (int k = 0; k < 2; ++k) dst[n][k] = *(const PG8_LAS bf16x8*)(lds + PG8_SB(b, h) + boff + n * 2048 + k * 1024); } while (0)
; #define PG8_MMA(ai, bj, At, Bt) do { __builtin_amdgcn_s_setprio(1); _Pragma("unroll") for (int m = 0; m < 4; ++m) _Pragma("unroll") for (int n = 0; n < 2; ++n) _Pragma("unroll") for (int k = 0; k < 2; ++k) \
;         acc[ai][bj][m][n] = __builtin_amdgcn_mfma_f32_16x16x32_bf16(Bt[n][k], At[m][k], acc[ai][bj][m][n], 0, 0, 0); __builtin_amdgcn_s_setprio(0); } while (0)
; #define PG8_WAIT_V(n) asm volatile("s_waitcnt vmcnt(" #n ")" ::: "memory")
; #define PG8_WAIT_L(n) asm volatile("s_waitcnt lgkmcnt(" #n ")" ::: "memory")
; #define PG8_BAR __builtin_amdgcn_s_barrier()
; template <class Epi, class Sched, bool ALIGN_EPI = false, bool SP2 = false>
; __device__ __forceinline__ void gemm_phase(PG8_LAS unsigned char* lds, const Gemm g, const Sched& S, const Epi& E, int wave_s) {
;     ...
;             const char* a1 = cA + (size_t)(t + 1) * kstep;
;             const char* a2 = last ? nA : cA + (size_t)(t + 2) * kstep; const char* b2 = last ? nB : cB + (size_t)(t + 2) * kstep;
;             const char* a3 = a2 + kstep; const char* b3 = b2 + kstep;
;             if (last && has_next) S.a_ready(nxt);
;             if constexpr (SP2) {
;             PG8_LDB(B0, 0, 0); PG8_LDB(B1, 0, 1); PG8_SCHED; PG8_LDA(At, 0, 0); PG8_STAGE(PG8_SA(1, 1), a1 + hstep, voffA);
;             PG8_WAIT_V(8); PG8_WAIT_L(0); PG8_BAR; PG8_MMA(0, 0, At, B0); PG8_MMA(0, 1, At, B1); PG8_BAR; PG8_SCHED;
;             PG8_LDA(At, 0, 1); PG8_STAGE(PG8_SB(0, 0), b2, voffB); PG8_STAGE(PG8_SB(0, 1), b2 + hstep, voffB); PG8_STAGE(PG8_SA(0, 0), a2, voffA);
;             PG8_WAIT_V(8); PG8_WAIT_L(0); PG8_BAR; PG8_MMA(1, 0, At, B0); PG8_MMA(1, 1, At, B1); PG8_BAR; PG8_SCHED;
.LBB0_1200:
	ds_read_b128 v[128:131], v211
	ds_read_b128 v[132:135], v211 offset:1024
	ds_read_b128 v[136:139], v211 offset:2048
	ds_read_b128 v[140:143], v211 offset:3072
	ds_read_b128 v[144:147], v212
	ds_read_b128 v[148:151], v212 offset:1024
	ds_read_b128 v[152:155], v212 offset:2048
	ds_read_b128 v[156:159], v212 offset:3072
	s_add_u32 s45, s50, 0xfff00080
	s_addc_u32 s52, s51, -1
	s_cmp_eq_u32 s85, s43
	s_cselect_b32 s55, s47, s52
	s_cselect_b32 s54, s46, s45
	s_cselect_b32 s53, s49, s41
	s_cselect_b32 s52, s48, s7
	s_nop 0
	s_add_i32 m0, s9, 0xc000
	ds_read_b128 v[160:163], v213
	ds_read_b128 v[164:167], v213 offset:1024
	ds_read_b128 v[168:171], v213 offset:2048
	ds_read_b128 v[172:175], v213 offset:3072
	ds_read_b128 v[176:179], v213 offset:4096
	ds_read_b128 v[180:183], v213 offset:5120
	ds_read_b128 v[196:199], v213 offset:6144
	ds_read_b128 v[200:203], v213 offset:7168
	global_load_lds_dwordx4 v192, s[50:51]
	s_nop 0
	s_add_i32 m0, s9, 0xe000
	s_nop 0
	global_load_lds_dwordx4 v194, s[50:51]
	s_waitcnt vmcnt(8)
	s_waitcnt lgkmcnt(0)
	s_barrier
	v_mfma_f32_16x16x32_bf16 v[124:127], v[128:131], v[160:163], v[124:127]
	v_mfma_f32_16x16x32_bf16 v[124:127], v[132:135], v[164:167], v[124:127]
	v_mfma_f32_16x16x32_bf16 v[120:123], v[140:143], v[164:167], v[120:123]
	v_mfma_f32_16x16x32_bf16 v[120:123], v[136:139], v[160:163], v[120:123]
	v_mfma_f32_16x16x32_bf16 v[104:107], v[136:139], v[168:171], v[104:107]
	v_mfma_f32_16x16x32_bf16 v[104:107], v[140:143], v[172:175], v[104:107]
	v_mfma_f32_16x16x32_bf16 v[108:111], v[132:135], v[172:175], v[108:111]
	v_mfma_f32_16x16x32_bf16 v[108:111], v[128:131], v[168:171], v[108:111]
	v_mfma_f32_16x16x32_bf16 v[92:95], v[128:131], v[176:179], v[92:95]
	v_mfma_f32_16x16x32_bf16 v[92:95], v[132:135], v[180:183], v[92:95]
	v_mfma_f32_16x16x32_bf16 v[88:91], v[140:143], v[180:183], v[88:91]
	v_mfma_f32_16x16x32_bf16 v[88:91], v[136:139], v[176:179], v[88:91]
	v_mfma_f32_16x16x32_bf16 v[72:75], v[136:139], v[196:199], v[72:75]
	v_mfma_f32_16x16x32_bf16 v[72:75], v[140:143], v[200:203], v[72:75]
	v_mfma_f32_16x16x32_bf16 v[76:79], v[132:135], v[200:203], v[76:79]
	v_mfma_f32_16x16x32_bf16 v[76:79], v[128:131], v[196:199], v[76:79]
	v_mfma_f32_16x16x32_bf16 v[116:119], v[144:147], v[160:163], v[116:119]
	v_mfma_f32_16x16x32_bf16 v[116:119], v[148:151], v[164:167], v[116:119]
	v_mfma_f32_16x16x32_bf16 v[112:115], v[156:159], v[164:167], v[112:115]
	v_mfma_f32_16x16x32_bf16 v[112:115], v[152:155], v[160:163], v[112:115]
	v_mfma_f32_16x16x32_bf16 v[96:99], v[152:155], v[168:171], v[96:99]
	v_mfma_f32_16x16x32_bf16 v[96:99], v[156:159], v[172:175], v[96:99]
	v_mfma_f32_16x16x32_bf16 v[100:103], v[148:151], v[172:175], v[100:103]
	v_mfma_f32_16x16x32_bf16 v[100:103], v[144:147], v[168:171], v[100:103]
	v_mfma_f32_16x16x32_bf16 v[84:87], v[144:147], v[176:179], v[84:87]
	v_mfma_f32_16x16x32_bf16 v[84:87], v[148:151], v[180:183], v[84:87]
	v_mfma_f32_16x16x32_bf16 v[80:83], v[156:159], v[180:183], v[80:83]
	v_mfma_f32_16x16x32_bf16 v[80:83], v[152:155], v[176:179], v[80:83]
	v_mfma_f32_16x16x32_bf16 v[64:67], v[152:155], v[196:199], v[64:67]
	v_mfma_f32_16x16x32_bf16 v[64:67], v[156:159], v[200:203], v[64:67]
	v_mfma_f32_16x16x32_bf16 v[68:71], v[148:151], v[200:203], v[68:71]
	v_mfma_f32_16x16x32_bf16 v[68:71], v[144:147], v[196:199], v[68:71]
	s_barrier
	s_add_i32 s45, s75, s60
	s_nop 0
	s_mov_b32 m0, s45
	ds_read_b128 v[160:163], v213 offset:16384
	ds_read_b128 v[164:167], v213 offset:17408
	ds_read_b128 v[168:171], v213 offset:18432
	ds_read_b128 v[172:175], v213 offset:19456
	ds_read_b128 v[176:179], v213 offset:20480
	ds_read_b128 v[180:183], v213 offset:21504
	ds_read_b128 v[196:199], v213 offset:22528
	ds_read_b128 v[200:203], v213 offset:23552
	global_load_lds_dwordx4 v186, s[52:53]
	s_add_i32 m0, s45, 0x2000
	s_add_u32 s86, s52, 0x100000
	s_nop 0
	s_addc_u32 s87, s53, 0
	s_add_i32 s45, s76, s60
	global_load_lds_dwordx4 v190, s[52:53]
	s_nop 0
	s_mov_b32 m0, s45
	s_nop 0
	global_load_lds_dwordx4 v186, s[86:87]
	s_nop 0
	s_add_i32 m0, s45, 0x2000
	s_nop 0
	global_load_lds_dwordx4 v190, s[86:87]
	s_nop 0
	s_mov_b32 m0, s9
	s_nop 0
	global_load_lds_dwordx4 v184, s[54:55]
	s_mov_b32 m0, s61
	s_nop 0
	global_load_lds_dwordx4 v188, s[54:55]
	s_waitcnt vmcnt(8)
	s_waitcnt lgkmcnt(0)
	s_barrier
	v_mfma_f32_16x16x32_bf16 v[60:63], v[128:131], v[160:163], v[60:63]
	v_mfma_f32_16x16x32_bf16 v[60:63], v[132:135], v[164:167], v[60:63]
	v_mfma_f32_16x16x32_bf16 v[56:59], v[140:143], v[164:167], v[56:59]
	v_mfma_f32_16x16x32_bf16 v[56:59], v[136:139], v[160:163], v[56:59]
	v_mfma_f32_16x16x32_bf16 v[40:43], v[136:139], v[168:171], v[40:43]
	v_mfma_f32_16x16x32_bf16 v[40:43], v[140:143], v[172:175], v[40:43]
	v_mfma_f32_16x16x32_bf16 v[44:47], v[132:135], v[172:175], v[44:47]
	v_mfma_f32_16x16x32_bf16 v[44:47], v[128:131], v[168:171], v[44:47]
	v_mfma_f32_16x16x32_bf16 v[28:31], v[128:131], v[176:179], v[28:31]
	v_mfma_f32_16x16x32_bf16 v[28:31], v[132:135], v[180:183], v[28:31]
	v_mfma_f32_16x16x32_bf16 v[24:27], v[140:143], v[180:183], v[24:27]
	v_mfma_f32_16x16x32_bf16 v[24:27], v[136:139], v[176:179], v[24:27]
	v_mfma_f32_16x16x32_bf16 v[8:11], v[136:139], v[196:199], v[8:11]
	v_mfma_f32_16x16x32_bf16 v[8:11], v[140:143], v[200:203], v[8:11]
	v_mfma_f32_16x16x32_bf16 v[12:15], v[132:135], v[200:203], v[12:15]
	v_mfma_f32_16x16x32_bf16 v[12:15], v[128:131], v[196:199], v[12:15]
	v_mfma_f32_16x16x32_bf16 v[52:55], v[144:147], v[160:163], v[52:55]
	v_mfma_f32_16x16x32_bf16 v[52:55], v[148:151], v[164:167], v[52:55]
	v_mfma_f32_16x16x32_bf16 v[48:51], v[156:159], v[164:167], v[48:51]
	v_mfma_f32_16x16x32_bf16 v[48:51], v[152:155], v[160:163], v[48:51]
	v_mfma_f32_16x16x32_bf16 v[32:35], v[152:155], v[168:171], v[32:35]
	v_mfma_f32_16x16x32_bf16 v[32:35], v[156:159], v[172:175], v[32:35]
	v_mfma_f32_16x16x32_bf16 v[36:39], v[148:151], v[172:175], v[36:39]
	v_mfma_f32_16x16x32_bf16 v[36:39], v[144:147], v[168:171], v[36:39]
	v_mfma_f32_16x16x32_bf16 v[20:23], v[144:147], v[176:179], v[20:23]
	v_mfma_f32_16x16x32_bf16 v[20:23], v[148:151], v[180:183], v[20:23]
	v_mfma_f32_16x16x32_bf16 v[16:19], v[156:159], v[180:183], v[16:19]
	v_mfma_f32_16x16x32_bf16 v[16:19], v[152:155], v[176:179], v[16:19]
	v_mfma_f32_16x16x32_bf16 v[0:3], v[152:155], v[196:199], v[0:3]
	v_mfma_f32_16x16x32_bf16 v[0:3], v[156:159], v[200:203], v[0:3]
	v_mfma_f32_16x16x32_bf16 v[4:7], v[148:151], v[200:203], v[4:7]
	v_mfma_f32_16x16x32_bf16 v[4:7], v[144:147], v[196:199], v[4:7]
	s_barrier
; #define PG8_LAS __attribute__((address_space(3)))
; #define PG8_STAGE(bufoff, gbase, voff) do { _Pragma("unroll") for (int _i = 0; _i < 2; ++_i) \
;         __builtin_amdgcn_global_load_lds((const unsigned*)((const char*)(gbase) + (voff)[_i]), (PG8_LAS unsigned*)(lds + (bufoff) + ldsw + _i * 8192), 16, 0, 0); } while (0)
; #define PG8_LDA(dst, b, h) do { _Pragma("unroll") for (int m = 0; m < 4; ++m) _Pragma("unroll") for (int k = 0; k < 2; ++k) dst[m][k] = *(const PG8_LAS bf16x8*)(lds + PG8_SA(b, h) + aoff + m * 2048 + k * 1024); } while (0)
; #define PG8_LDB(dst, b, h) do { _Pragma("unroll") for (int n = 0; n < 2; ++n) _Pragma("unroll") for (int k = 0; k < 2; ++k) dst[n][k] = *(const PG8_LAS bf16x8*)(lds + PG8_SB(b, h) + boff + n * 2048 + k * 1024); } while (0)
; #define PG8_WAIT_V(n) asm volatile("s_waitcnt vmcnt(" #n ")" ::: "memory")
; #define PG8_WAIT_L(n) asm volatile("s_waitcnt lgkmcnt(" #n ")" ::: "memory")
; #define PG8_BAR __builtin_amdgcn_s_barrier()
; #define PG8_SCHED __builtin_amdgcn_sched_barrier(0)
; template <class Epi, class Sched, bool ALIGN_EPI = false, bool SP2 = false>
; __device__ __forceinline__ void gemm_phase(PG8_LAS unsigned char* lds, const Gemm g, const Sched& S, const Epi& E, int wave_s) {
;     ...
;         for (int t = 0; t < nt; t += 2) {
;             const bool last = (t == nt - 2);
;             if constexpr (Epi::NEED_RS) { if (t == 0 && wid < 4) __builtin_amdgcn_global_load_lds((const unsigned*)(E.rstd + cur.pm * BM + wid * 64 + lane), (PG8_LAS unsigned*)(rsl + wid * 64), 4, 0, 0); }
;             const char* a1 = cA + (size_t)(t + 1) * kstep;
;             const char* a2 = last ? nA : cA + (size_t)(t + 2) * kstep; const char* b2 = last ? nB : cB + (size_t)(t + 2) * kstep;
;             const char* a3 = a2 + kstep; const char* b3 = b2 + kstep;
;     ...
;             PG8_LDB(B0, 1, 0); PG8_LDB(B1, 1, 1); PG8_SCHED; PG8_LDA(At, 1, 0); PG8_STAGE(PG8_SA(0, 1), a2 + hstep, voffA);
;             PG8_WAIT_V(8); PG8_WAIT_L(0); PG8_BAR; PG8_MMA(0, 0, At, B0); PG8_MMA(0, 1, At, B1); PG8_BAR; PG8_SCHED;
;             PG8_LDA(At, 1, 1); PG8_STAGE(PG8_SB(1, 0), b3, voffB); PG8_STAGE(PG8_SB(1, 1), b3 + hstep, voffB); PG8_STAGE(PG8_SA(1, 0), a3, voffA);
;             PG8_WAIT_V(8); PG8_WAIT_L(0); PG8_BAR; PG8_MMA(1, 0, At, B0); PG8_MMA(1, 1, At, B1); PG8_BAR; PG8_SCHED;
	s_add_i32 s45, 0, 0x18000
	s_add_i32 s86, 0, 0x1c000
	v_add_u32_e32 v140, s45, v210
	v_add_u32_e32 v156, s86, v210
	ds_read_b128 v[128:131], v140
	ds_read_b128 v[132:135], v140 offset:1024
	ds_read_b128 v[136:139], v140 offset:2048
	ds_read_b128 v[140:143], v140 offset:3072
	ds_read_b128 v[144:147], v156
	ds_read_b128 v[148:151], v156 offset:1024
	ds_read_b128 v[152:155], v156 offset:2048
	ds_read_b128 v[156:159], v156 offset:3072
	s_add_u32 s54, s54, 0x100000
	s_addc_u32 s55, s55, 0
	s_mov_b32 m0, s62
	s_nop 0
	ds_read_b128 v[160:163], v213 offset:32768
	ds_read_b128 v[164:167], v213 offset:33792
	ds_read_b128 v[168:171], v213 offset:34816
	ds_read_b128 v[172:175], v213 offset:35840
	ds_read_b128 v[176:179], v213 offset:36864
	ds_read_b128 v[180:183], v213 offset:37888
	ds_read_b128 v[196:199], v213 offset:38912
	ds_read_b128 v[200:203], v213 offset:39936
	global_load_lds_dwordx4 v184, s[54:55]
	s_nop 0
	s_mov_b32 m0, s63
	s_nop 0
	global_load_lds_dwordx4 v188, s[54:55]
	s_waitcnt vmcnt(8)
	s_waitcnt lgkmcnt(0)
	s_barrier
	v_mfma_f32_16x16x32_bf16 v[124:127], v[128:131], v[160:163], v[124:127]
	v_mfma_f32_16x16x32_bf16 v[124:127], v[132:135], v[164:167], v[124:127]
	v_mfma_f32_16x16x32_bf16 v[120:123], v[140:143], v[164:167], v[120:123]
	v_mfma_f32_16x16x32_bf16 v[120:123], v[136:139], v[160:163], v[120:123]
	v_mfma_f32_16x16x32_bf16 v[104:107], v[136:139], v[168:171], v[104:107]
	v_mfma_f32_16x16x32_bf16 v[104:107], v[140:143], v[172:175], v[104:107]
	v_mfma_f32_16x16x32_bf16 v[108:111], v[132:135], v[172:175], v[108:111]
	v_mfma_f32_16x16x32_bf16 v[108:111], v[128:131], v[168:171], v[108:111]
	v_mfma_f32_16x16x32_bf16 v[92:95], v[128:131], v[176:179], v[92:95]
	v_mfma_f32_16x16x32_bf16 v[92:95], v[132:135], v[180:183], v[92:95]
	v_mfma_f32_16x16x32_bf16 v[88:91], v[140:143], v[180:183], v[88:91]
	v_mfma_f32_16x16x32_bf16 v[88:91], v[136:139], v[176:179], v[88:91]
	v_mfma_f32_16x16x32_bf16 v[72:75], v[136:139], v[196:199], v[72:75]
	v_mfma_f32_16x16x32_bf16 v[72:75], v[140:143], v[200:203], v[72:75]
	v_mfma_f32_16x16x32_bf16 v[76:79], v[132:135], v[200:203], v[76:79]
	v_mfma_f32_16x16x32_bf16 v[76:79], v[128:131], v[196:199], v[76:79]
	v_mfma_f32_16x16x32_bf16 v[116:119], v[144:147], v[160:163], v[116:119]
	v_mfma_f32_16x16x32_bf16 v[116:119], v[148:151], v[164:167], v[116:119]
	v_mfma_f32_16x16x32_bf16 v[112:115], v[156:159], v[164:167], v[112:115]
	v_mfma_f32_16x16x32_bf16 v[112:115], v[152:155], v[160:163], v[112:115]
	v_mfma_f32_16x16x32_bf16 v[96:99], v[152:155], v[168:171], v[96:99]
	v_mfma_f32_16x16x32_bf16 v[96:99], v[156:159], v[172:175], v[96:99]
	v_mfma_f32_16x16x32_bf16 v[100:103], v[148:151], v[172:175], v[100:103]
	v_mfma_f32_16x16x32_bf16 v[100:103], v[144:147], v[168:171], v[100:103]
	v_mfma_f32_16x16x32_bf16 v[84:87], v[144:147], v[176:179], v[84:87]
	v_mfma_f32_16x16x32_bf16 v[84:87], v[148:151], v[180:183], v[84:87]
	v_mfma_f32_16x16x32_bf16 v[80:83], v[156:159], v[180:183], v[80:83]
	v_mfma_f32_16x16x32_bf16 v[80:83], v[152:155], v[176:179], v[80:83]
	v_mfma_f32_16x16x32_bf16 v[64:67], v[152:155], v[196:199], v[64:67]
	v_mfma_f32_16x16x32_bf16 v[64:67], v[156:159], v[200:203], v[64:67]
	v_mfma_f32_16x16x32_bf16 v[68:71], v[148:151], v[200:203], v[68:71]
	v_mfma_f32_16x16x32_bf16 v[68:71], v[144:147], v[196:199], v[68:71]
	s_barrier
	s_add_i32 s45, s45, s60
	s_nop 0
	s_mov_b32 m0, s45
	ds_read_b128 v[160:163], v213 offset:49152
	ds_read_b128 v[164:167], v213 offset:50176
	ds_read_b128 v[168:171], v213 offset:51200
	ds_read_b128 v[172:175], v213 offset:52224
	ds_read_b128 v[176:179], v213 offset:53248
	ds_read_b128 v[180:183], v213 offset:54272
	ds_read_b128 v[196:199], v213 offset:55296
	ds_read_b128 v[200:203], v213 offset:56320
	s_add_u32 s94, s52, 0x80
	s_addc_u32 s95, s53, 0
	global_load_lds_dwordx4 v186, s[94:95]
	s_add_i32 m0, s45, 0x2000
	s_add_u32 s52, s52, 0x100080
	s_nop 0
	s_addc_u32 s53, s53, 0
	s_add_i32 s45, s86, s60
	global_load_lds_dwordx4 v190, s[94:95]
	s_nop 0
	s_mov_b32 m0, s45
	s_nop 0
	global_load_lds_dwordx4 v186, s[52:53]
	s_nop 0
	s_add_i32 m0, s45, 0x2000
	s_nop 0
	global_load_lds_dwordx4 v190, s[52:53]
	s_nop 0
	s_mov_b32 m0, s70
	s_nop 0
	s_add_u32 s96, s54, 0xfff00080
	s_addc_u32 s97, s55, -1
	global_load_lds_dwordx4 v184, s[96:97]
	s_nop 0
	s_mov_b32 m0, s71
	s_nop 0
	global_load_lds_dwordx4 v188, s[96:97]
	s_waitcnt vmcnt(8)
	s_waitcnt lgkmcnt(0)
	s_barrier
	v_mfma_f32_16x16x32_bf16 v[60:63], v[128:131], v[160:163], v[60:63]
	v_mfma_f32_16x16x32_bf16 v[60:63], v[132:135], v[164:167], v[60:63]
	v_mfma_f32_16x16x32_bf16 v[56:59], v[140:143], v[164:167], v[56:59]
	v_mfma_f32_16x16x32_bf16 v[56:59], v[136:139], v[160:163], v[56:59]
	v_mfma_f32_16x16x32_bf16 v[40:43], v[136:139], v[168:171], v[40:43]
	v_mfma_f32_16x16x32_bf16 v[40:43], v[140:143], v[172:175], v[40:43]
	v_mfma_f32_16x16x32_bf16 v[44:47], v[132:135], v[172:175], v[44:47]
	v_mfma_f32_16x16x32_bf16 v[44:47], v[128:131], v[168:171], v[44:47]
	v_mfma_f32_16x16x32_bf16 v[28:31], v[128:131], v[176:179], v[28:31]
	v_mfma_f32_16x16x32_bf16 v[28:31], v[132:135], v[180:183], v[28:31]
	v_mfma_f32_16x16x32_bf16 v[24:27], v[140:143], v[180:183], v[24:27]
	v_mfma_f32_16x16x32_bf16 v[24:27], v[136:139], v[176:179], v[24:27]
	v_mfma_f32_16x16x32_bf16 v[8:11], v[136:139], v[196:199], v[8:11]
	v_mfma_f32_16x16x32_bf16 v[8:11], v[140:143], v[200:203], v[8:11]
	v_mfma_f32_16x16x32_bf16 v[12:15], v[132:135], v[200:203], v[12:15]
	v_mfma_f32_16x16x32_bf16 v[12:15], v[128:131], v[196:199], v[12:15]
	v_mfma_f32_16x16x32_bf16 v[52:55], v[144:147], v[160:163], v[52:55]
	v_mfma_f32_16x16x32_bf16 v[52:55], v[148:151], v[164:167], v[52:55]
	v_mfma_f32_16x16x32_bf16 v[48:51], v[156:159], v[164:167], v[48:51]
	v_mfma_f32_16x16x32_bf16 v[48:51], v[152:155], v[160:163], v[48:51]
	v_mfma_f32_16x16x32_bf16 v[32:35], v[152:155], v[168:171], v[32:35]
	v_mfma_f32_16x16x32_bf16 v[32:35], v[156:159], v[172:175], v[32:35]
	v_mfma_f32_16x16x32_bf16 v[36:39], v[148:151], v[172:175], v[36:39]
	v_mfma_f32_16x16x32_bf16 v[36:39], v[144:147], v[168:171], v[36:39]
	v_mfma_f32_16x16x32_bf16 v[20:23], v[144:147], v[176:179], v[20:23]
	v_mfma_f32_16x16x32_bf16 v[20:23], v[148:151], v[180:183], v[20:23]
	v_mfma_f32_16x16x32_bf16 v[16:19], v[156:159], v[180:183], v[16:19]
	v_mfma_f32_16x16x32_bf16 v[16:19], v[152:155], v[176:179], v[16:19]
	v_mfma_f32_16x16x32_bf16 v[0:3], v[152:155], v[196:199], v[0:3]
	v_mfma_f32_16x16x32_bf16 v[0:3], v[156:159], v[200:203], v[0:3]
	v_mfma_f32_16x16x32_bf16 v[4:7], v[148:151], v[200:203], v[4:7]
	v_mfma_f32_16x16x32_bf16 v[4:7], v[144:147], v[196:199], v[4:7]
	s_barrier
	s_add_i32 s45, s43, 2
	s_add_u32 s50, s50, 0x100
	s_addc_u32 s51, s51, 0
	s_add_u32 s7, s7, 0x100
	s_addc_u32 s41, s41, 0
	s_cmp_ge_i32 s43, s85
	s_mov_b32 s43, s45
	s_cbranch_scc0 .LBB0_1200
	s_and_b64 vcc, exec, s[20:21]
	s_cbranch_vccz .LBB0_1203
	s_barrier

; #define PG8_STAGE(bufoff, gbase, voff) do { _Pragma("unroll") for (int _i = 0; _i < 2; ++_i) \
;         __builtin_amdgcn_global_load_lds((const unsigned*)((const char*)(gbase) + (voff)[_i]), (PG8_LAS unsigned*)(lds + (bufoff) + ldsw + _i * 8192), 16, 0, 0); } while (0)
; #define PG8_LDA(dst, b, h) do { _Pragma("unroll") for (int m = 0; m < 4; ++m) _Pragma("unroll") for (int k = 0; k < 2; ++k) dst[m][k] = *(const PG8_LAS bf16x8*)(lds + PG8_SA(b, h) + aoff + m * 2048 + k * 1024); } while (0)
; #define PG8_LDB(dst, b, h) do { _Pragma("unroll") for (int n = 0; n < 2; ++n) _Pragma("unroll") for (int k = 0; k < 2; ++k) dst[n][k] = *(const PG8_LAS bf16x8*)(lds + PG8_SB(b, h) + boff + n * 2048 + k * 1024); } while (0)
; #define PG8_MMA(ai, bj, At, Bt) do { __builtin_amdgcn_s_setprio(1); _Pragma("unroll") for (int m = 0; m < 4; ++m) _Pragma("unroll") for (int n = 0; n < 2; ++n) _Pragma("unroll") for (int k = 0; k < 2; ++k) \
;         acc[ai][bj][m][n] = __builtin_amdgcn_mfma_f32_16x16x32_bf16(Bt[n][k], At[m][k], acc[ai][bj][m][n], 0, 0, 0); __builtin_amdgcn_s_setprio(0); } while (0)
; #define PG8_WAIT_V(n) asm volatile("s_waitcnt vmcnt(" #n ")" ::: "memory")
; #define PG8_WAIT_L(n) asm volatile("s_waitcnt lgkmcnt(" #n ")" ::: "memory")
; #define PG8_BAR __builtin_amdgcn_s_barrier()
; template <class Epi, class Sched, bool ALIGN_EPI = false, bool SP2 = false>
; __device__ __forceinline__ void gemm_phase(PG8_LAS unsigned char* lds, const Gemm g, const Sched& S, const Epi& E, int wave_s) {
;     ...
;             const char* a1 = cA + (size_t)(t + 1) * kstep;
;             const char* a2 = last ? nA : cA + (size_t)(t + 2) * kstep; const char* b2 = last ? nB : cB + (size_t)(t + 2) * kstep;
;             const char* a3 = a2 + kstep; const char* b3 = b2 + kstep;
;             if (last && has_next) S.a_ready(nxt);
;             if constexpr (SP2) {
;             PG8_LDB(B0, 0, 0); PG8_LDB(B1, 0, 1); PG8_SCHED; PG8_LDA(At, 0, 0); PG8_STAGE(PG8_SA(1, 1), a1 + hstep, voffA);
;             PG8_WAIT_V(8); PG8_WAIT_L(0); PG8_BAR; PG8_MMA(0, 0, At, B0); PG8_MMA(0, 1, At, B1); PG8_BAR; PG8_SCHED;
;             PG8_LDA(At, 0, 1); PG8_STAGE(PG8_SB(0, 0), b2, voffB); PG8_STAGE(PG8_SB(0, 1), b2 + hstep, voffB); PG8_STAGE(PG8_SA(0, 0), a2, voffA);
;             PG8_WAIT_V(8); PG8_WAIT_L(0); PG8_BAR; PG8_MMA(1, 0, At, B0); PG8_MMA(1, 1, At, B1); PG8_BAR; PG8_SCHED;
.LBB0_1343:
	ds_read_b128 v[144:147], v150 offset:3072
	ds_read_b128 v[152:155], v150 offset:2048
	ds_read_b128 v[156:159], v150 offset:1024
	ds_read_b128 v[160:163], v150
	ds_read_b128 v[164:167], v149 offset:3072
	ds_read_b128 v[168:171], v149 offset:2048
	ds_read_b128 v[172:175], v149 offset:1024
	ds_read_b128 v[176:179], v149
	s_add_u32 s46, s44, 0xfff00080
	s_addc_u32 s47, s45, -1
	s_cmp_eq_u32 s88, 60
	s_cselect_b32 s49, s29, s47
	s_cselect_b32 s48, s74, s46
	s_cselect_b32 s47, s35, s87
	s_cselect_b32 s46, s75, s86
	s_mov_b32 m0, s76
	s_nop 0
	ds_read_b128 v[180:183], v151
	ds_read_b128 v[184:187], v151 offset:1024
	ds_read_b128 v[188:191], v151 offset:2048
	ds_read_b128 v[192:195], v151 offset:3072
	ds_read_b128 v[196:199], v151 offset:4096
	ds_read_b128 v[200:203], v151 offset:5120
	ds_read_b128 v[204:207], v151 offset:6144
	ds_read_b128 v[208:211], v151 offset:7168
	global_load_lds_dwordx4 v138, s[44:45]
	s_nop 0
	s_mov_b32 m0, s77
	s_nop 0
	global_load_lds_dwordx4 v140, s[44:45]
	s_waitcnt vmcnt(8)
	s_waitcnt lgkmcnt(0)
	s_barrier
	v_mfma_f32_16x16x32_bf16 v[124:127], v[176:179], v[180:183], v[124:127]
	v_mfma_f32_16x16x32_bf16 v[124:127], v[172:175], v[184:187], v[124:127]
	v_mfma_f32_16x16x32_bf16 v[120:123], v[164:167], v[184:187], v[120:123]
	v_mfma_f32_16x16x32_bf16 v[120:123], v[168:171], v[180:183], v[120:123]
	v_mfma_f32_16x16x32_bf16 v[104:107], v[168:171], v[188:191], v[104:107]
	v_mfma_f32_16x16x32_bf16 v[104:107], v[164:167], v[192:195], v[104:107]
	v_mfma_f32_16x16x32_bf16 v[108:111], v[172:175], v[192:195], v[108:111]
	v_mfma_f32_16x16x32_bf16 v[108:111], v[176:179], v[188:191], v[108:111]
	v_mfma_f32_16x16x32_bf16 v[92:95], v[176:179], v[196:199], v[92:95]
	v_mfma_f32_16x16x32_bf16 v[92:95], v[172:175], v[200:203], v[92:95]
	v_mfma_f32_16x16x32_bf16 v[88:91], v[164:167], v[200:203], v[88:91]
	v_mfma_f32_16x16x32_bf16 v[88:91], v[168:171], v[196:199], v[88:91]
	v_mfma_f32_16x16x32_bf16 v[72:75], v[168:171], v[204:207], v[72:75]
	v_mfma_f32_16x16x32_bf16 v[72:75], v[164:167], v[208:211], v[72:75]
	v_mfma_f32_16x16x32_bf16 v[76:79], v[172:175], v[208:211], v[76:79]
	v_mfma_f32_16x16x32_bf16 v[76:79], v[176:179], v[204:207], v[76:79]
	v_mfma_f32_16x16x32_bf16 v[116:119], v[160:163], v[180:183], v[116:119]
	v_mfma_f32_16x16x32_bf16 v[116:119], v[156:159], v[184:187], v[116:119]
	v_mfma_f32_16x16x32_bf16 v[112:115], v[144:147], v[184:187], v[112:115]
	v_mfma_f32_16x16x32_bf16 v[112:115], v[152:155], v[180:183], v[112:115]
	v_mfma_f32_16x16x32_bf16 v[96:99], v[152:155], v[188:191], v[96:99]
	v_mfma_f32_16x16x32_bf16 v[96:99], v[144:147], v[192:195], v[96:99]
	v_mfma_f32_16x16x32_bf16 v[100:103], v[156:159], v[192:195], v[100:103]
	v_mfma_f32_16x16x32_bf16 v[100:103], v[160:163], v[188:191], v[100:103]
	v_mfma_f32_16x16x32_bf16 v[84:87], v[160:163], v[196:199], v[84:87]
	v_mfma_f32_16x16x32_bf16 v[84:87], v[156:159], v[200:203], v[84:87]
	v_mfma_f32_16x16x32_bf16 v[80:83], v[144:147], v[200:203], v[80:83]
	v_mfma_f32_16x16x32_bf16 v[80:83], v[152:155], v[196:199], v[80:83]
	v_mfma_f32_16x16x32_bf16 v[64:67], v[152:155], v[204:207], v[64:67]
	v_mfma_f32_16x16x32_bf16 v[64:67], v[144:147], v[208:211], v[64:67]
	v_mfma_f32_16x16x32_bf16 v[68:71], v[156:159], v[208:211], v[68:71]
	v_mfma_f32_16x16x32_bf16 v[68:71], v[160:163], v[204:207], v[68:71]
	s_barrier
	s_mov_b32 m0, s78
	s_nop 0
	s_add_u32 s90, s46, 0x100000
	ds_read_b128 v[180:183], v151 offset:16384
	ds_read_b128 v[184:187], v151 offset:17408
	ds_read_b128 v[188:191], v151 offset:18432
	ds_read_b128 v[192:195], v151 offset:19456
	ds_read_b128 v[196:199], v151 offset:20480
	ds_read_b128 v[200:203], v151 offset:21504
	ds_read_b128 v[204:207], v151 offset:22528
	ds_read_b128 v[208:211], v151 offset:23552
	global_load_lds_dwordx4 v132, s[46:47]
	s_nop 0
	s_mov_b32 m0, s79
	s_addc_u32 s91, s47, 0
	global_load_lds_dwordx4 v128, s[46:47]
	s_nop 0
	s_mov_b32 m0, s80
	s_nop 0
	global_load_lds_dwordx4 v132, s[90:91]
	s_nop 0
	s_mov_b32 m0, s81
	s_nop 0
	global_load_lds_dwordx4 v128, s[90:91]
	s_nop 0
	s_mov_b32 m0, s41
	s_nop 0
	global_load_lds_dwordx4 v134, s[48:49]
	s_mov_b32 m0, s43
	s_nop 0
	global_load_lds_dwordx4 v130, s[48:49]
	s_waitcnt vmcnt(8)
	s_waitcnt lgkmcnt(0)
	s_barrier
	v_mfma_f32_16x16x32_bf16 v[60:63], v[176:179], v[180:183], v[60:63]
	v_mfma_f32_16x16x32_bf16 v[60:63], v[172:175], v[184:187], v[60:63]
	v_mfma_f32_16x16x32_bf16 v[56:59], v[164:167], v[184:187], v[56:59]
	v_mfma_f32_16x16x32_bf16 v[56:59], v[168:171], v[180:183], v[56:59]
	v_mfma_f32_16x16x32_bf16 v[40:43], v[168:171], v[188:191], v[40:43]
	v_mfma_f32_16x16x32_bf16 v[40:43], v[164:167], v[192:195], v[40:43]
	v_mfma_f32_16x16x32_bf16 v[44:47], v[172:175], v[192:195], v[44:47]
	v_mfma_f32_16x16x32_bf16 v[44:47], v[176:179], v[188:191], v[44:47]
	v_mfma_f32_16x16x32_bf16 v[28:31], v[176:179], v[196:199], v[28:31]
	v_mfma_f32_16x16x32_bf16 v[28:31], v[172:175], v[200:203], v[28:31]
	v_mfma_f32_16x16x32_bf16 v[24:27], v[164:167], v[200:203], v[24:27]
	v_mfma_f32_16x16x32_bf16 v[24:27], v[168:171], v[196:199], v[24:27]
	v_mfma_f32_16x16x32_bf16 v[8:11], v[168:171], v[204:207], v[8:11]
	v_mfma_f32_16x16x32_bf16 v[8:11], v[164:167], v[208:211], v[8:11]
	v_mfma_f32_16x16x32_bf16 v[12:15], v[172:175], v[208:211], v[12:15]
	v_mfma_f32_16x16x32_bf16 v[12:15], v[176:179], v[204:207], v[12:15]
	v_mfma_f32_16x16x32_bf16 v[52:55], v[160:163], v[180:183], v[52:55]
	v_mfma_f32_16x16x32_bf16 v[52:55], v[156:159], v[184:187], v[52:55]
	v_mfma_f32_16x16x32_bf16 v[48:51], v[144:147], v[184:187], v[48:51]
	v_mfma_f32_16x16x32_bf16 v[48:51], v[152:155], v[180:183], v[48:51]
	v_mfma_f32_16x16x32_bf16 v[32:35], v[152:155], v[188:191], v[32:35]
	v_mfma_f32_16x16x32_bf16 v[32:35], v[144:147], v[192:195], v[32:35]
	v_mfma_f32_16x16x32_bf16 v[36:39], v[156:159], v[192:195], v[36:39]
	v_mfma_f32_16x16x32_bf16 v[36:39], v[160:163], v[188:191], v[36:39]
	v_mfma_f32_16x16x32_bf16 v[20:23], v[160:163], v[196:199], v[20:23]
	v_mfma_f32_16x16x32_bf16 v[20:23], v[156:159], v[200:203], v[20:23]
	v_mfma_f32_16x16x32_bf16 v[16:19], v[144:147], v[200:203], v[16:19]
	v_mfma_f32_16x16x32_bf16 v[16:19], v[152:155], v[196:199], v[16:19]
	v_mfma_f32_16x16x32_bf16 v[0:3], v[152:155], v[204:207], v[0:3]
	v_mfma_f32_16x16x32_bf16 v[0:3], v[144:147], v[208:211], v[0:3]
	v_mfma_f32_16x16x32_bf16 v[4:7], v[156:159], v[208:211], v[4:7]
	v_mfma_f32_16x16x32_bf16 v[4:7], v[160:163], v[204:207], v[4:7]
	s_barrier
; #define PG8_LAS __attribute__((address_space(3)))
; #define PG8_STAGE(bufoff, gbase, voff) do { _Pragma("unroll") for (int _i = 0; _i < 2; ++_i) \
;         __builtin_amdgcn_global_load_lds((const unsigned*)((const char*)(gbase) + (voff)[_i]), (PG8_LAS unsigned*)(lds + (bufoff) + ldsw + _i * 8192), 16, 0, 0); } while (0)
; #define PG8_LDA(dst, b, h) do { _Pragma("unroll") for (int m = 0; m < 4; ++m) _Pragma("unroll") for (int k = 0; k < 2; ++k) dst[m][k] = *(const PG8_LAS bf16x8*)(lds + PG8_SA(b, h) + aoff + m * 2048 + k * 1024); } while (0)
; #define PG8_LDB(dst, b, h) do { _Pragma("unroll") for (int n = 0; n < 2; ++n) _Pragma("unroll") for (int k = 0; k < 2; ++k) dst[n][k] = *(const PG8_LAS bf16x8*)(lds + PG8_SB(b, h) + boff + n * 2048 + k * 1024); } while (0)
; #define PG8_WAIT_V(n) asm volatile("s_waitcnt vmcnt(" #n ")" ::: "memory")
; #define PG8_WAIT_L(n) asm volatile("s_waitcnt lgkmcnt(" #n ")" ::: "memory")
; #define PG8_BAR __builtin_amdgcn_s_barrier()
; #define PG8_SCHED __builtin_amdgcn_sched_barrier(0)
; template <class Epi, class Sched, bool ALIGN_EPI = false, bool SP2 = false>
; __device__ __forceinline__ void gemm_phase(PG8_LAS unsigned char* lds, const Gemm g, const Sched& S, const Epi& E, int wave_s) {
;     ...
;         for (int t = 0; t < nt; t += 2) {
;             const bool last = (t == nt - 2);
;             if constexpr (Epi::NEED_RS) { if (t == 0 && wid < 4) __builtin_amdgcn_global_load_lds((const unsigned*)(E.rstd + cur.pm * BM + wid * 64 + lane), (PG8_LAS unsigned*)(rsl + wid * 64), 4, 0, 0); }
;             const char* a1 = cA + (size_t)(t + 1) * kstep;
;             const char* a2 = last ? nA : cA + (size_t)(t + 2) * kstep; const char* b2 = last ? nB : cB + (size_t)(t + 2) * kstep;
;             const char* a3 = a2 + kstep; const char* b3 = b2 + kstep;
;     ...
;             PG8_LDB(B0, 1, 0); PG8_LDB(B1, 1, 1); PG8_SCHED; PG8_LDA(At, 1, 0); PG8_STAGE(PG8_SA(0, 1), a2 + hstep, voffA);
;             PG8_WAIT_V(8); PG8_WAIT_L(0); PG8_BAR; PG8_MMA(0, 0, At, B0); PG8_MMA(0, 1, At, B1); PG8_BAR; PG8_SCHED;
;             PG8_LDA(At, 1, 1); PG8_STAGE(PG8_SB(1, 0), b3, voffB); PG8_STAGE(PG8_SB(1, 1), b3 + hstep, voffB); PG8_STAGE(PG8_SA(1, 0), a3, voffA);
;             PG8_WAIT_V(8); PG8_WAIT_L(0); PG8_BAR; PG8_MMA(1, 0, At, B0); PG8_MMA(1, 1, At, B1); PG8_BAR; PG8_SCHED;
	ds_read_b128 v[144:147], v142
	ds_read_b128 v[152:155], v142 offset:1024
	ds_read_b128 v[156:159], v142 offset:2048
	ds_read_b128 v[160:163], v142 offset:3072
	ds_read_b128 v[164:167], v143
	ds_read_b128 v[168:171], v143 offset:1024
	ds_read_b128 v[172:175], v143 offset:2048
	ds_read_b128 v[176:179], v143 offset:3072
	s_add_u32 s48, s48, 0x100000
	s_addc_u32 s49, s49, 0
	s_mov_b32 m0, s58
	s_nop 0
	ds_read_b128 v[180:183], v151 offset:32768
	ds_read_b128 v[184:187], v151 offset:33792
	ds_read_b128 v[188:191], v151 offset:34816
	ds_read_b128 v[192:195], v151 offset:35840
	ds_read_b128 v[196:199], v151 offset:36864
	ds_read_b128 v[200:203], v151 offset:37888
	ds_read_b128 v[204:207], v151 offset:38912
	ds_read_b128 v[208:211], v151 offset:39936
	global_load_lds_dwordx4 v134, s[48:49]
	s_nop 0
	s_mov_b32 m0, s59
	s_nop 0
	global_load_lds_dwordx4 v130, s[48:49]
	s_waitcnt vmcnt(8)
	s_waitcnt lgkmcnt(0)
	s_barrier
	v_mfma_f32_16x16x32_bf16 v[124:127], v[144:147], v[180:183], v[124:127]
	v_mfma_f32_16x16x32_bf16 v[124:127], v[152:155], v[184:187], v[124:127]
	v_mfma_f32_16x16x32_bf16 v[120:123], v[160:163], v[184:187], v[120:123]
	v_mfma_f32_16x16x32_bf16 v[120:123], v[156:159], v[180:183], v[120:123]
	v_mfma_f32_16x16x32_bf16 v[104:107], v[156:159], v[188:191], v[104:107]
	v_mfma_f32_16x16x32_bf16 v[104:107], v[160:163], v[192:195], v[104:107]
	v_mfma_f32_16x16x32_bf16 v[108:111], v[152:155], v[192:195], v[108:111]
	v_mfma_f32_16x16x32_bf16 v[108:111], v[144:147], v[188:191], v[108:111]
	v_mfma_f32_16x16x32_bf16 v[92:95], v[144:147], v[196:199], v[92:95]
	v_mfma_f32_16x16x32_bf16 v[92:95], v[152:155], v[200:203], v[92:95]
	v_mfma_f32_16x16x32_bf16 v[88:91], v[160:163], v[200:203], v[88:91]
	v_mfma_f32_16x16x32_bf16 v[88:91], v[156:159], v[196:199], v[88:91]
	v_mfma_f32_16x16x32_bf16 v[72:75], v[156:159], v[204:207], v[72:75]
	v_mfma_f32_16x16x32_bf16 v[72:75], v[160:163], v[208:211], v[72:75]
	v_mfma_f32_16x16x32_bf16 v[76:79], v[152:155], v[208:211], v[76:79]
	v_mfma_f32_16x16x32_bf16 v[76:79], v[144:147], v[204:207], v[76:79]
	v_mfma_f32_16x16x32_bf16 v[116:119], v[164:167], v[180:183], v[116:119]
	v_mfma_f32_16x16x32_bf16 v[116:119], v[168:171], v[184:187], v[116:119]
	v_mfma_f32_16x16x32_bf16 v[112:115], v[176:179], v[184:187], v[112:115]
	v_mfma_f32_16x16x32_bf16 v[112:115], v[172:175], v[180:183], v[112:115]
	v_mfma_f32_16x16x32_bf16 v[96:99], v[172:175], v[188:191], v[96:99]
	v_mfma_f32_16x16x32_bf16 v[96:99], v[176:179], v[192:195], v[96:99]
	v_mfma_f32_16x16x32_bf16 v[100:103], v[168:171], v[192:195], v[100:103]
	v_mfma_f32_16x16x32_bf16 v[100:103], v[164:167], v[188:191], v[100:103]
	v_mfma_f32_16x16x32_bf16 v[84:87], v[164:167], v[196:199], v[84:87]
	v_mfma_f32_16x16x32_bf16 v[84:87], v[168:171], v[200:203], v[84:87]
	v_mfma_f32_16x16x32_bf16 v[80:83], v[176:179], v[200:203], v[80:83]
	v_mfma_f32_16x16x32_bf16 v[80:83], v[172:175], v[196:199], v[80:83]
	v_mfma_f32_16x16x32_bf16 v[64:67], v[172:175], v[204:207], v[64:67]
	v_mfma_f32_16x16x32_bf16 v[64:67], v[176:179], v[208:211], v[64:67]
	v_mfma_f32_16x16x32_bf16 v[68:71], v[168:171], v[208:211], v[68:71]
	v_mfma_f32_16x16x32_bf16 v[68:71], v[164:167], v[204:207], v[68:71]
	s_barrier
	s_mov_b32 m0, s82
	s_nop 0
	s_add_u32 s94, s46, 0x80
	s_addc_u32 s95, s47, 0
	s_add_u32 s46, s46, 0x100080
	ds_read_b128 v[180:183], v151 offset:49152
	ds_read_b128 v[184:187], v151 offset:50176
	ds_read_b128 v[188:191], v151 offset:51200
	ds_read_b128 v[192:195], v151 offset:52224
	ds_read_b128 v[196:199], v151 offset:53248
	ds_read_b128 v[200:203], v151 offset:54272
	ds_read_b128 v[204:207], v151 offset:55296
	ds_read_b128 v[208:211], v151 offset:56320
	global_load_lds_dwordx4 v132, s[94:95]
	s_nop 0
	s_mov_b32 m0, s83
	s_addc_u32 s47, s47, 0
	global_load_lds_dwordx4 v128, s[94:95]
	s_nop 0
	s_mov_b32 m0, s84
	s_nop 0
	global_load_lds_dwordx4 v132, s[46:47]
	s_nop 0
	s_mov_b32 m0, s85
	s_nop 0
	global_load_lds_dwordx4 v128, s[46:47]
	s_nop 0
	s_mov_b32 m0, s62
	s_nop 0
	s_add_u32 s96, s48, 0xfff00080
	s_addc_u32 s97, s49, -1
	global_load_lds_dwordx4 v134, s[96:97]
	s_nop 0
	s_mov_b32 m0, s63
	s_nop 0
	global_load_lds_dwordx4 v130, s[96:97]
	s_waitcnt vmcnt(8)
	s_waitcnt lgkmcnt(0)
	s_barrier
	v_mfma_f32_16x16x32_bf16 v[60:63], v[144:147], v[180:183], v[60:63]
	v_mfma_f32_16x16x32_bf16 v[60:63], v[152:155], v[184:187], v[60:63]
	v_mfma_f32_16x16x32_bf16 v[56:59], v[160:163], v[184:187], v[56:59]
	v_mfma_f32_16x16x32_bf16 v[56:59], v[156:159], v[180:183], v[56:59]
	v_mfma_f32_16x16x32_bf16 v[40:43], v[156:159], v[188:191], v[40:43]
	v_mfma_f32_16x16x32_bf16 v[40:43], v[160:163], v[192:195], v[40:43]
	v_mfma_f32_16x16x32_bf16 v[44:47], v[152:155], v[192:195], v[44:47]
	v_mfma_f32_16x16x32_bf16 v[44:47], v[144:147], v[188:191], v[44:47]
	v_mfma_f32_16x16x32_bf16 v[28:31], v[144:147], v[196:199], v[28:31]
	v_mfma_f32_16x16x32_bf16 v[28:31], v[152:155], v[200:203], v[28:31]
	v_mfma_f32_16x16x32_bf16 v[24:27], v[160:163], v[200:203], v[24:27]
	v_mfma_f32_16x16x32_bf16 v[24:27], v[156:159], v[196:199], v[24:27]
	v_mfma_f32_16x16x32_bf16 v[8:11], v[156:159], v[204:207], v[8:11]
	v_mfma_f32_16x16x32_bf16 v[8:11], v[160:163], v[208:211], v[8:11]
	v_mfma_f32_16x16x32_bf16 v[12:15], v[152:155], v[208:211], v[12:15]
	v_mfma_f32_16x16x32_bf16 v[12:15], v[144:147], v[204:207], v[12:15]
	v_mfma_f32_16x16x32_bf16 v[52:55], v[164:167], v[180:183], v[52:55]
	v_mfma_f32_16x16x32_bf16 v[52:55], v[168:171], v[184:187], v[52:55]
	v_mfma_f32_16x16x32_bf16 v[48:51], v[176:179], v[184:187], v[48:51]
	v_mfma_f32_16x16x32_bf16 v[48:51], v[172:175], v[180:183], v[48:51]
	v_mfma_f32_16x16x32_bf16 v[32:35], v[172:175], v[188:191], v[32:35]
	v_mfma_f32_16x16x32_bf16 v[32:35], v[176:179], v[192:195], v[32:35]
	v_mfma_f32_16x16x32_bf16 v[36:39], v[168:171], v[192:195], v[36:39]
	v_mfma_f32_16x16x32_bf16 v[36:39], v[164:167], v[188:191], v[36:39]
	v_mfma_f32_16x16x32_bf16 v[20:23], v[164:167], v[196:199], v[20:23]
	v_mfma_f32_16x16x32_bf16 v[20:23], v[168:171], v[200:203], v[20:23]
	v_mfma_f32_16x16x32_bf16 v[16:19], v[176:179], v[200:203], v[16:19]
	v_mfma_f32_16x16x32_bf16 v[16:19], v[172:175], v[196:199], v[16:19]
	v_mfma_f32_16x16x32_bf16 v[0:3], v[172:175], v[204:207], v[0:3]
	v_mfma_f32_16x16x32_bf16 v[0:3], v[176:179], v[208:211], v[0:3]
	v_mfma_f32_16x16x32_bf16 v[4:7], v[168:171], v[208:211], v[4:7]
	v_mfma_f32_16x16x32_bf16 v[4:7], v[164:167], v[204:207], v[4:7]
	s_barrier
	s_add_i32 s88, s88, 2
	s_add_u32 s44, s44, 0x100
	s_addc_u32 s45, s45, 0
	s_add_u32 s86, s86, 0x100
	s_addc_u32 s87, s87, 0
	s_cmp_gt_u32 s88, 61
	s_cbranch_scc0 .LBB0_1343
	s_and_b64 vcc, exec, s[14:15]
	s_cbranch_vccz .LBB0_1346
	s_barrier

; #define PG8_STAGE(bufoff, gbase, voff) do { _Pragma("unroll") for (int _i = 0; _i < 2; ++_i) \
;         __builtin_amdgcn_global_load_lds((const unsigned*)((const char*)(gbase) + (voff)[_i]), (PG8_LAS unsigned*)(lds + (bufoff) + ldsw + _i * 8192), 16, 0, 0); } while (0)
; #define PG8_LDA(dst, b, h) do { _Pragma("unroll") for (int m = 0; m < 4; ++m) _Pragma("unroll") for (int k = 0; k < 2; ++k) dst[m][k] = *(const PG8_LAS bf16x8*)(lds + PG8_SA(b, h) + aoff + m * 2048 + k * 1024); } while (0)
; #define PG8_LDB(dst, b, h) do { _Pragma("unroll") for (int n = 0; n < 2; ++n) _Pragma("unroll") for (int k = 0; k < 2; ++k) dst[n][k] = *(const PG8_LAS bf16x8*)(lds + PG8_SB(b, h) + boff + n * 2048 + k * 1024); } while (0)
; #define PG8_MMA(ai, bj, At, Bt) do { __builtin_amdgcn_s_setprio(1); _Pragma("unroll") for (int m = 0; m < 4; ++m) _Pragma("unroll") for (int n = 0; n < 2; ++n) _Pragma("unroll") for (int k = 0; k < 2; ++k) \
;         acc[ai][bj][m][n] = __builtin_amdgcn_mfma_f32_16x16x32_bf16(Bt[n][k], At[m][k], acc[ai][bj][m][n], 0, 0, 0); __builtin_amdgcn_s_setprio(0); } while (0)
; #define PG8_WAIT_V(n) asm volatile("s_waitcnt vmcnt(" #n ")" ::: "memory")
; #define PG8_WAIT_L(n) asm volatile("s_waitcnt lgkmcnt(" #n ")" ::: "memory")
; #define PG8_BAR __builtin_amdgcn_s_barrier()
; template <class Epi, class Sched, bool ALIGN_EPI = false, bool SP2 = false>
; __device__ __forceinline__ void gemm_phase(PG8_LAS unsigned char* lds, const Gemm g, const Sched& S, const Epi& E, int wave_s) {
;     ...
;             const char* a1 = cA + (size_t)(t + 1) * kstep;
;             const char* a2 = last ? nA : cA + (size_t)(t + 2) * kstep; const char* b2 = last ? nB : cB + (size_t)(t + 2) * kstep;
;             const char* a3 = a2 + kstep; const char* b3 = b2 + kstep;
;             if (last && has_next) S.a_ready(nxt);
;             if constexpr (SP2) {
;             PG8_LDB(B0, 0, 0); PG8_LDB(B1, 0, 1); PG8_SCHED; PG8_LDA(At, 0, 0); PG8_STAGE(PG8_SA(1, 1), a1 + hstep, voffA);
;             PG8_WAIT_V(8); PG8_WAIT_L(0); PG8_BAR; PG8_MMA(0, 0, At, B0); PG8_MMA(0, 1, At, B1); PG8_BAR; PG8_SCHED;
;             PG8_LDA(At, 0, 1); PG8_STAGE(PG8_SB(0, 0), b2, voffB); PG8_STAGE(PG8_SB(0, 1), b2 + hstep, voffB); PG8_STAGE(PG8_SA(0, 0), a2, voffA);
;             PG8_WAIT_V(8); PG8_WAIT_L(0); PG8_BAR; PG8_MMA(1, 0, At, B0); PG8_MMA(1, 1, At, B1); PG8_BAR; PG8_SCHED;
.LBB0_1410:
	ds_read_b128 v[128:131], v211
	ds_read_b128 v[132:135], v211 offset:1024
	ds_read_b128 v[136:139], v211 offset:2048
	ds_read_b128 v[140:143], v211 offset:3072
	ds_read_b128 v[144:147], v212
	ds_read_b128 v[148:151], v212 offset:1024
	ds_read_b128 v[152:155], v212 offset:2048
	ds_read_b128 v[156:159], v212 offset:3072
	s_add_u32 s45, s50, 0xffc00080
	s_addc_u32 s52, s51, -1
	s_cmp_eq_u32 s85, s43
	s_cselect_b32 s55, s47, s52
	s_cselect_b32 s54, s46, s45
	s_cselect_b32 s53, s49, s41
	s_cselect_b32 s52, s48, s7
	s_nop 0
	s_add_i32 m0, s9, 0xc000
	ds_read_b128 v[160:163], v213
	ds_read_b128 v[164:167], v213 offset:1024
	ds_read_b128 v[168:171], v213 offset:2048
	ds_read_b128 v[172:175], v213 offset:3072
	ds_read_b128 v[176:179], v213 offset:4096
	ds_read_b128 v[180:183], v213 offset:5120
	ds_read_b128 v[196:199], v213 offset:6144
	ds_read_b128 v[200:203], v213 offset:7168
	global_load_lds_dwordx4 v192, s[50:51]
	s_nop 0
	s_add_i32 m0, s9, 0xe000
	s_nop 0
	global_load_lds_dwordx4 v194, s[50:51]
	s_waitcnt vmcnt(8)
	s_waitcnt lgkmcnt(0)
	s_barrier
	v_mfma_f32_16x16x32_bf16 v[124:127], v[128:131], v[160:163], v[124:127]
	v_mfma_f32_16x16x32_bf16 v[124:127], v[132:135], v[164:167], v[124:127]
	v_mfma_f32_16x16x32_bf16 v[120:123], v[140:143], v[164:167], v[120:123]
	v_mfma_f32_16x16x32_bf16 v[120:123], v[136:139], v[160:163], v[120:123]
	v_mfma_f32_16x16x32_bf16 v[104:107], v[136:139], v[168:171], v[104:107]
	v_mfma_f32_16x16x32_bf16 v[104:107], v[140:143], v[172:175], v[104:107]
	v_mfma_f32_16x16x32_bf16 v[108:111], v[132:135], v[172:175], v[108:111]
	v_mfma_f32_16x16x32_bf16 v[108:111], v[128:131], v[168:171], v[108:111]
	v_mfma_f32_16x16x32_bf16 v[92:95], v[128:131], v[176:179], v[92:95]
	v_mfma_f32_16x16x32_bf16 v[92:95], v[132:135], v[180:183], v[92:95]
	v_mfma_f32_16x16x32_bf16 v[88:91], v[140:143], v[180:183], v[88:91]
	v_mfma_f32_16x16x32_bf16 v[88:91], v[136:139], v[176:179], v[88:91]
	v_mfma_f32_16x16x32_bf16 v[72:75], v[136:139], v[196:199], v[72:75]
	v_mfma_f32_16x16x32_bf16 v[72:75], v[140:143], v[200:203], v[72:75]
	v_mfma_f32_16x16x32_bf16 v[76:79], v[132:135], v[200:203], v[76:79]
	v_mfma_f32_16x16x32_bf16 v[76:79], v[128:131], v[196:199], v[76:79]
	v_mfma_f32_16x16x32_bf16 v[116:119], v[144:147], v[160:163], v[116:119]
	v_mfma_f32_16x16x32_bf16 v[116:119], v[148:151], v[164:167], v[116:119]
	v_mfma_f32_16x16x32_bf16 v[112:115], v[156:159], v[164:167], v[112:115]
	v_mfma_f32_16x16x32_bf16 v[112:115], v[152:155], v[160:163], v[112:115]
	v_mfma_f32_16x16x32_bf16 v[96:99], v[152:155], v[168:171], v[96:99]
	v_mfma_f32_16x16x32_bf16 v[96:99], v[156:159], v[172:175], v[96:99]
	v_mfma_f32_16x16x32_bf16 v[100:103], v[148:151], v[172:175], v[100:103]
	v_mfma_f32_16x16x32_bf16 v[100:103], v[144:147], v[168:171], v[100:103]
	v_mfma_f32_16x16x32_bf16 v[84:87], v[144:147], v[176:179], v[84:87]
	v_mfma_f32_16x16x32_bf16 v[84:87], v[148:151], v[180:183], v[84:87]
	v_mfma_f32_16x16x32_bf16 v[80:83], v[156:159], v[180:183], v[80:83]
	v_mfma_f32_16x16x32_bf16 v[80:83], v[152:155], v[176:179], v[80:83]
	v_mfma_f32_16x16x32_bf16 v[64:67], v[152:155], v[196:199], v[64:67]
	v_mfma_f32_16x16x32_bf16 v[64:67], v[156:159], v[200:203], v[64:67]
	v_mfma_f32_16x16x32_bf16 v[68:71], v[148:151], v[200:203], v[68:71]
	v_mfma_f32_16x16x32_bf16 v[68:71], v[144:147], v[196:199], v[68:71]
	s_barrier
	s_add_i32 s45, s75, s60
	s_nop 0
	s_mov_b32 m0, s45
	ds_read_b128 v[160:163], v213 offset:16384
	ds_read_b128 v[164:167], v213 offset:17408
	ds_read_b128 v[168:171], v213 offset:18432
	ds_read_b128 v[172:175], v213 offset:19456
	ds_read_b128 v[176:179], v213 offset:20480
	ds_read_b128 v[180:183], v213 offset:21504
	ds_read_b128 v[196:199], v213 offset:22528
	ds_read_b128 v[200:203], v213 offset:23552
	global_load_lds_dwordx4 v186, s[52:53]
	s_add_i32 m0, s45, 0x2000
	s_add_u32 s86, s52, 0x400000
	s_nop 0
	s_addc_u32 s87, s53, 0
	s_add_i32 s45, s76, s60
	global_load_lds_dwordx4 v190, s[52:53]
	s_nop 0
	s_mov_b32 m0, s45
	s_nop 0
	global_load_lds_dwordx4 v186, s[86:87]
	s_nop 0
	s_add_i32 m0, s45, 0x2000
	s_nop 0
	global_load_lds_dwordx4 v190, s[86:87]
	s_nop 0
	s_mov_b32 m0, s9
	s_nop 0
	global_load_lds_dwordx4 v184, s[54:55]
	s_mov_b32 m0, s61
	s_nop 0
	global_load_lds_dwordx4 v188, s[54:55]
	s_waitcnt vmcnt(8)
	s_waitcnt lgkmcnt(0)
	s_barrier
	v_mfma_f32_16x16x32_bf16 v[60:63], v[128:131], v[160:163], v[60:63]
	v_mfma_f32_16x16x32_bf16 v[60:63], v[132:135], v[164:167], v[60:63]
	v_mfma_f32_16x16x32_bf16 v[56:59], v[140:143], v[164:167], v[56:59]
	v_mfma_f32_16x16x32_bf16 v[56:59], v[136:139], v[160:163], v[56:59]
	v_mfma_f32_16x16x32_bf16 v[40:43], v[136:139], v[168:171], v[40:43]
	v_mfma_f32_16x16x32_bf16 v[40:43], v[140:143], v[172:175], v[40:43]
	v_mfma_f32_16x16x32_bf16 v[44:47], v[132:135], v[172:175], v[44:47]
	v_mfma_f32_16x16x32_bf16 v[44:47], v[128:131], v[168:171], v[44:47]
	v_mfma_f32_16x16x32_bf16 v[28:31], v[128:131], v[176:179], v[28:31]
	v_mfma_f32_16x16x32_bf16 v[28:31], v[132:135], v[180:183], v[28:31]
	v_mfma_f32_16x16x32_bf16 v[24:27], v[140:143], v[180:183], v[24:27]
	v_mfma_f32_16x16x32_bf16 v[24:27], v[136:139], v[176:179], v[24:27]
	v_mfma_f32_16x16x32_bf16 v[8:11], v[136:139], v[196:199], v[8:11]
	v_mfma_f32_16x16x32_bf16 v[8:11], v[140:143], v[200:203], v[8:11]
	v_mfma_f32_16x16x32_bf16 v[12:15], v[132:135], v[200:203], v[12:15]
	v_mfma_f32_16x16x32_bf16 v[12:15], v[128:131], v[196:199], v[12:15]
	v_mfma_f32_16x16x32_bf16 v[52:55], v[144:147], v[160:163], v[52:55]
	v_mfma_f32_16x16x32_bf16 v[52:55], v[148:151], v[164:167], v[52:55]
	v_mfma_f32_16x16x32_bf16 v[48:51], v[156:159], v[164:167], v[48:51]
	v_mfma_f32_16x16x32_bf16 v[48:51], v[152:155], v[160:163], v[48:51]
	v_mfma_f32_16x16x32_bf16 v[32:35], v[152:155], v[168:171], v[32:35]
	v_mfma_f32_16x16x32_bf16 v[32:35], v[156:159], v[172:175], v[32:35]
	v_mfma_f32_16x16x32_bf16 v[36:39], v[148:151], v[172:175], v[36:39]
	v_mfma_f32_16x16x32_bf16 v[36:39], v[144:147], v[168:171], v[36:39]
	v_mfma_f32_16x16x32_bf16 v[20:23], v[144:147], v[176:179], v[20:23]
	v_mfma_f32_16x16x32_bf16 v[20:23], v[148:151], v[180:183], v[20:23]
	v_mfma_f32_16x16x32_bf16 v[16:19], v[156:159], v[180:183], v[16:19]
	v_mfma_f32_16x16x32_bf16 v[16:19], v[152:155], v[176:179], v[16:19]
	v_mfma_f32_16x16x32_bf16 v[0:3], v[152:155], v[196:199], v[0:3]
	v_mfma_f32_16x16x32_bf16 v[0:3], v[156:159], v[200:203], v[0:3]
	v_mfma_f32_16x16x32_bf16 v[4:7], v[148:151], v[200:203], v[4:7]
	v_mfma_f32_16x16x32_bf16 v[4:7], v[144:147], v[196:199], v[4:7]
	s_barrier
; #define PG8_LAS __attribute__((address_space(3)))
; #define PG8_STAGE(bufoff, gbase, voff) do { _Pragma("unroll") for (int _i = 0; _i < 2; ++_i) \
;         __builtin_amdgcn_global_load_lds((const unsigned*)((const char*)(gbase) + (voff)[_i]), (PG8_LAS unsigned*)(lds + (bufoff) + ldsw + _i * 8192), 16, 0, 0); } while (0)
; #define PG8_LDA(dst, b, h) do { _Pragma("unroll") for (int m = 0; m < 4; ++m) _Pragma("unroll") for (int k = 0; k < 2; ++k) dst[m][k] = *(const PG8_LAS bf16x8*)(lds + PG8_SA(b, h) + aoff + m * 2048 + k * 1024); } while (0)
; #define PG8_LDB(dst, b, h) do { _Pragma("unroll") for (int n = 0; n < 2; ++n) _Pragma("unroll") for (int k = 0; k < 2; ++k) dst[n][k] = *(const PG8_LAS bf16x8*)(lds + PG8_SB(b, h) + boff + n * 2048 + k * 1024); } while (0)
; #define PG8_WAIT_V(n) asm volatile("s_waitcnt vmcnt(" #n ")" ::: "memory")
; #define PG8_WAIT_L(n) asm volatile("s_waitcnt lgkmcnt(" #n ")" ::: "memory")
; #define PG8_BAR __builtin_amdgcn_s_barrier()
; #define PG8_SCHED __builtin_amdgcn_sched_barrier(0)
; template <class Epi, class Sched, bool ALIGN_EPI = false, bool SP2 = false>
; __device__ __forceinline__ void gemm_phase(PG8_LAS unsigned char* lds, const Gemm g, const Sched& S, const Epi& E, int wave_s) {
;     ...
;         for (int t = 0; t < nt; t += 2) {
;             const bool last = (t == nt - 2);
;             if constexpr (Epi::NEED_RS) { if (t == 0 && wid < 4) __builtin_amdgcn_global_load_lds((const unsigned*)(E.rstd + cur.pm * BM + wid * 64 + lane), (PG8_LAS unsigned*)(rsl + wid * 64), 4, 0, 0); }
;             const char* a1 = cA + (size_t)(t + 1) * kstep;
;             const char* a2 = last ? nA : cA + (size_t)(t + 2) * kstep; const char* b2 = last ? nB : cB + (size_t)(t + 2) * kstep;
;             const char* a3 = a2 + kstep; const char* b3 = b2 + kstep;
;     ...
;             PG8_LDB(B0, 1, 0); PG8_LDB(B1, 1, 1); PG8_SCHED; PG8_LDA(At, 1, 0); PG8_STAGE(PG8_SA(0, 1), a2 + hstep, voffA);
;             PG8_WAIT_V(8); PG8_WAIT_L(0); PG8_BAR; PG8_MMA(0, 0, At, B0); PG8_MMA(0, 1, At, B1); PG8_BAR; PG8_SCHED;
;             PG8_LDA(At, 1, 1); PG8_STAGE(PG8_SB(1, 0), b3, voffB); PG8_STAGE(PG8_SB(1, 1), b3 + hstep, voffB); PG8_STAGE(PG8_SA(1, 0), a3, voffA);
;             PG8_WAIT_V(8); PG8_WAIT_L(0); PG8_BAR; PG8_MMA(1, 0, At, B0); PG8_MMA(1, 1, At, B1); PG8_BAR; PG8_SCHED;
	s_add_i32 s45, 0, 0x18000
	s_add_i32 s86, 0, 0x1c000
	v_add_u32_e32 v140, s45, v210
	v_add_u32_e32 v156, s86, v210
	ds_read_b128 v[128:131], v140
	ds_read_b128 v[132:135], v140 offset:1024
	ds_read_b128 v[136:139], v140 offset:2048
	ds_read_b128 v[140:143], v140 offset:3072
	ds_read_b128 v[144:147], v156
	ds_read_b128 v[148:151], v156 offset:1024
	ds_read_b128 v[152:155], v156 offset:2048
	ds_read_b128 v[156:159], v156 offset:3072
	s_add_u32 s54, s54, 0x400000
	s_addc_u32 s55, s55, 0
	s_mov_b32 m0, s62
	s_nop 0
	ds_read_b128 v[160:163], v213 offset:32768
	ds_read_b128 v[164:167], v213 offset:33792
	ds_read_b128 v[168:171], v213 offset:34816
	ds_read_b128 v[172:175], v213 offset:35840
	ds_read_b128 v[176:179], v213 offset:36864
	ds_read_b128 v[180:183], v213 offset:37888
	ds_read_b128 v[196:199], v213 offset:38912
	ds_read_b128 v[200:203], v213 offset:39936
	global_load_lds_dwordx4 v184, s[54:55]
	s_nop 0
	s_mov_b32 m0, s63
	s_nop 0
	global_load_lds_dwordx4 v188, s[54:55]
	s_waitcnt vmcnt(8)
	s_waitcnt lgkmcnt(0)
	s_barrier
	v_mfma_f32_16x16x32_bf16 v[124:127], v[128:131], v[160:163], v[124:127]
	v_mfma_f32_16x16x32_bf16 v[124:127], v[132:135], v[164:167], v[124:127]
	v_mfma_f32_16x16x32_bf16 v[120:123], v[140:143], v[164:167], v[120:123]
	v_mfma_f32_16x16x32_bf16 v[120:123], v[136:139], v[160:163], v[120:123]
	v_mfma_f32_16x16x32_bf16 v[104:107], v[136:139], v[168:171], v[104:107]
	v_mfma_f32_16x16x32_bf16 v[104:107], v[140:143], v[172:175], v[104:107]
	v_mfma_f32_16x16x32_bf16 v[108:111], v[132:135], v[172:175], v[108:111]
	v_mfma_f32_16x16x32_bf16 v[108:111], v[128:131], v[168:171], v[108:111]
	v_mfma_f32_16x16x32_bf16 v[92:95], v[128:131], v[176:179], v[92:95]
	v_mfma_f32_16x16x32_bf16 v[92:95], v[132:135], v[180:183], v[92:95]
	v_mfma_f32_16x16x32_bf16 v[88:91], v[140:143], v[180:183], v[88:91]
	v_mfma_f32_16x16x32_bf16 v[88:91], v[136:139], v[176:179], v[88:91]
	v_mfma_f32_16x16x32_bf16 v[72:75], v[136:139], v[196:199], v[72:75]
	v_mfma_f32_16x16x32_bf16 v[72:75], v[140:143], v[200:203], v[72:75]
	v_mfma_f32_16x16x32_bf16 v[76:79], v[132:135], v[200:203], v[76:79]
	v_mfma_f32_16x16x32_bf16 v[76:79], v[128:131], v[196:199], v[76:79]
	v_mfma_f32_16x16x32_bf16 v[116:119], v[144:147], v[160:163], v[116:119]
	v_mfma_f32_16x16x32_bf16 v[116:119], v[148:151], v[164:167], v[116:119]
	v_mfma_f32_16x16x32_bf16 v[112:115], v[156:159], v[164:167], v[112:115]
	v_mfma_f32_16x16x32_bf16 v[112:115], v[152:155], v[160:163], v[112:115]
	v_mfma_f32_16x16x32_bf16 v[96:99], v[152:155], v[168:171], v[96:99]
	v_mfma_f32_16x16x32_bf16 v[96:99], v[156:159], v[172:175], v[96:99]
	v_mfma_f32_16x16x32_bf16 v[100:103], v[148:151], v[172:175], v[100:103]
	v_mfma_f32_16x16x32_bf16 v[100:103], v[144:147], v[168:171], v[100:103]
	v_mfma_f32_16x16x32_bf16 v[84:87], v[144:147], v[176:179], v[84:87]
	v_mfma_f32_16x16x32_bf16 v[84:87], v[148:151], v[180:183], v[84:87]
	v_mfma_f32_16x16x32_bf16 v[80:83], v[156:159], v[180:183], v[80:83]
	v_mfma_f32_16x16x32_bf16 v[80:83], v[152:155], v[176:179], v[80:83]
	v_mfma_f32_16x16x32_bf16 v[64:67], v[152:155], v[196:199], v[64:67]
	v_mfma_f32_16x16x32_bf16 v[64:67], v[156:159], v[200:203], v[64:67]
	v_mfma_f32_16x16x32_bf16 v[68:71], v[148:151], v[200:203], v[68:71]
	v_mfma_f32_16x16x32_bf16 v[68:71], v[144:147], v[196:199], v[68:71]
	s_barrier
	s_add_i32 s45, s45, s60
	s_nop 0
	s_mov_b32 m0, s45
	ds_read_b128 v[160:163], v213 offset:49152
	ds_read_b128 v[164:167], v213 offset:50176
	ds_read_b128 v[168:171], v213 offset:51200
	ds_read_b128 v[172:175], v213 offset:52224
	ds_read_b128 v[176:179], v213 offset:53248
	ds_read_b128 v[180:183], v213 offset:54272
	ds_read_b128 v[196:199], v213 offset:55296
	ds_read_b128 v[200:203], v213 offset:56320
	s_add_u32 s94, s52, 0x80
	s_addc_u32 s95, s53, 0
	global_load_lds_dwordx4 v186, s[94:95]
	s_add_i32 m0, s45, 0x2000
	s_add_u32 s52, s52, 0x400080
	s_nop 0
	s_addc_u32 s53, s53, 0
	s_add_i32 s45, s86, s60
	global_load_lds_dwordx4 v190, s[94:95]
	s_nop 0
	s_mov_b32 m0, s45
	s_nop 0
	global_load_lds_dwordx4 v186, s[52:53]
	s_nop 0
	s_add_i32 m0, s45, 0x2000
	s_nop 0
	global_load_lds_dwordx4 v190, s[52:53]
	s_nop 0
	s_mov_b32 m0, s70
	s_nop 0
	s_add_u32 s96, s54, 0xffc00080
	s_addc_u32 s97, s55, -1
	global_load_lds_dwordx4 v184, s[96:97]
	s_nop 0
	s_mov_b32 m0, s71
	s_nop 0
	global_load_lds_dwordx4 v188, s[96:97]
	s_waitcnt vmcnt(8)
	s_waitcnt lgkmcnt(0)
	s_barrier
	v_mfma_f32_16x16x32_bf16 v[60:63], v[128:131], v[160:163], v[60:63]
	v_mfma_f32_16x16x32_bf16 v[60:63], v[132:135], v[164:167], v[60:63]
	v_mfma_f32_16x16x32_bf16 v[56:59], v[140:143], v[164:167], v[56:59]
	v_mfma_f32_16x16x32_bf16 v[56:59], v[136:139], v[160:163], v[56:59]
	v_mfma_f32_16x16x32_bf16 v[40:43], v[136:139], v[168:171], v[40:43]
	v_mfma_f32_16x16x32_bf16 v[40:43], v[140:143], v[172:175], v[40:43]
	v_mfma_f32_16x16x32_bf16 v[44:47], v[132:135], v[172:175], v[44:47]
	v_mfma_f32_16x16x32_bf16 v[44:47], v[128:131], v[168:171], v[44:47]
	v_mfma_f32_16x16x32_bf16 v[28:31], v[128:131], v[176:179], v[28:31]
	v_mfma_f32_16x16x32_bf16 v[28:31], v[132:135], v[180:183], v[28:31]
	v_mfma_f32_16x16x32_bf16 v[24:27], v[140:143], v[180:183], v[24:27]
	v_mfma_f32_16x16x32_bf16 v[24:27], v[136:139], v[176:179], v[24:27]
	v_mfma_f32_16x16x32_bf16 v[8:11], v[136:139], v[196:199], v[8:11]
	v_mfma_f32_16x16x32_bf16 v[8:11], v[140:143], v[200:203], v[8:11]
	v_mfma_f32_16x16x32_bf16 v[12:15], v[132:135], v[200:203], v[12:15]
	v_mfma_f32_16x16x32_bf16 v[12:15], v[128:131], v[196:199], v[12:15]
	v_mfma_f32_16x16x32_bf16 v[52:55], v[144:147], v[160:163], v[52:55]
	v_mfma_f32_16x16x32_bf16 v[52:55], v[148:151], v[164:167], v[52:55]
	v_mfma_f32_16x16x32_bf16 v[48:51], v[156:159], v[164:167], v[48:51]
	v_mfma_f32_16x16x32_bf16 v[48:51], v[152:155], v[160:163], v[48:51]
	v_mfma_f32_16x16x32_bf16 v[32:35], v[152:155], v[168:171], v[32:35]
	v_mfma_f32_16x16x32_bf16 v[32:35], v[156:159], v[172:175], v[32:35]
	v_mfma_f32_16x16x32_bf16 v[36:39], v[148:151], v[172:175], v[36:39]
	v_mfma_f32_16x16x32_bf16 v[36:39], v[144:147], v[168:171], v[36:39]
	v_mfma_f32_16x16x32_bf16 v[20:23], v[144:147], v[176:179], v[20:23]
	v_mfma_f32_16x16x32_bf16 v[20:23], v[148:151], v[180:183], v[20:23]
	v_mfma_f32_16x16x32_bf16 v[16:19], v[156:159], v[180:183], v[16:19]
	v_mfma_f32_16x16x32_bf16 v[16:19], v[152:155], v[176:179], v[16:19]
	v_mfma_f32_16x16x32_bf16 v[0:3], v[152:155], v[196:199], v[0:3]
	v_mfma_f32_16x16x32_bf16 v[0:3], v[156:159], v[200:203], v[0:3]
	v_mfma_f32_16x16x32_bf16 v[4:7], v[148:151], v[200:203], v[4:7]
	v_mfma_f32_16x16x32_bf16 v[4:7], v[144:147], v[196:199], v[4:7]
	s_barrier
	s_add_i32 s45, s43, 2
	s_add_u32 s50, s50, 0x100
	s_addc_u32 s51, s51, 0
	s_add_u32 s7, s7, 0x100
	s_addc_u32 s41, s41, 0
	s_cmp_ge_i32 s43, s85
	s_mov_b32 s43, s45
	s_cbranch_scc0 .LBB0_1410
	s_and_b64 vcc, exec, s[20:21]
	s_cbranch_vccz .LBB0_1413
	s_barrier
